# attention pair jobs: only tile B's exponentials streamed into the P V steps, tile A's stay ahead of the V phase
# speedup vs baseline: 1.0003x; 1.0003x over previous
.Latt_noedge_2:
	s_nop 1
	v_max3_f32 v186, v36, v37, v38
	v_max3_f32 v186, v186, v39, v40
	v_max3_f32 v186, v186, v41, v42
	v_max3_f32 v186, v186, v43, v44
	v_max3_f32 v186, v186, v45, v46
	v_max3_f32 v186, v186, v47, v48
	v_max3_f32 v186, v186, v49, v50
	v_max3_f32 v186, v186, v51, v52
	v_max3_f32 v186, v186, v53, v54
	v_max3_f32 v186, v186, v55, v56
	v_max3_f32 v186, v186, v57, v58
	v_max3_f32 v186, v186, v59, v60
	v_max3_f32 v186, v186, v61, v62
	v_max3_f32 v186, v186, v63, v64
	v_max3_f32 v186, v186, v65, v66
	v_max3_f32 v186, v186, v67, v68
	v_max3_f32 v186, v186, v69, v70
	v_max_f32_e32 v186, v186, v71
	v_mov_b32_e32 v146, v186
	s_nop 1
	v_permlane16_swap_b32_e32 v186, v146
	v_max_f32_e32 v186, v186, v146
	v_mov_b32_e32 v146, v186
	s_nop 1
	v_permlane32_swap_b32_e32 v186, v146
	v_max_f32_e32 v186, v186, v146
	s_waitcnt lgkmcnt(0)
	s_add_i32 s93, s76, 16
	s_mov_b32 m0, s14
	v_add_u32_e32 v164, s93, v231
	v_med3_i32 v164, v164, 0, s40
	v_lshl_or_b32 v164, v164, 7, v222
	global_load_lds_dwordx4 v164, s[24:25]
	s_add_i32 m0, s14, 0x400
	v_add_u32_e32 v165, s93, v232
	v_med3_i32 v165, v165, 0, s40
	v_lshl_or_b32 v165, v165, 7, v222
	global_load_lds_dwordx4 v165, s[24:25]
	s_waitcnt vmcnt(8)
	v_add_u32_e32 v154, s15, v225
	v_add_u32_e32 v155, s15, v226
	v_add_u32_e32 v156, s15, v227
	v_add_u32_e32 v157, s15, v228
	ds_read_b64_tr_b16 v[202:203], v154
	ds_read_b64_tr_b16 v[204:205], v155
	ds_read_b64_tr_b16 v[206:207], v156
	ds_read_b64_tr_b16 v[208:209], v157
	v_mfma_f32_16x16x16_bf16 v[96:99], v[88:89], v[0:1], 0
	v_mfma_f32_16x16x16_bf16 v[100:103], v[90:91], v[0:1], 0
	v_mfma_f32_16x16x16_bf16 v[104:107], v[92:93], v[0:1], 0
	v_mfma_f32_16x16x16_bf16 v[108:111], v[94:95], v[0:1], 0
	v_pk_add_f32 v[36:37], v[36:37], v[186:187] op_sel_hi:[1,0] neg_lo:[0,1] neg_hi:[0,1]
	v_pk_add_f32 v[38:39], v[38:39], v[186:187] op_sel_hi:[1,0] neg_lo:[0,1] neg_hi:[0,1]
	v_exp_f32_e32 v36, v36
	v_exp_f32_e32 v37, v37
	v_exp_f32_e32 v38, v38
	v_exp_f32_e32 v39, v39
	s_nop 0
	v_pk_add_f32 v[76:77], v[36:37], v[38:39]
	v_cvt_pk_bf16_f32 v36, v36, v37
	v_cvt_pk_bf16_f32 v37, v38, v39
	s_waitcnt lgkmcnt(0)
	s_add_i32 s93, s76, 32
	s_mov_b32 m0, s15
	v_add_u32_e32 v164, s93, v231
	v_med3_i32 v164, v164, 0, s40
	v_lshl_or_b32 v164, v164, 7, v222
	global_load_lds_dwordx4 v164, s[24:25]
	s_add_i32 m0, s15, 0x400
	v_add_u32_e32 v165, s93, v232
	v_med3_i32 v165, v165, 0, s40
	v_lshl_or_b32 v165, v165, 7, v222
	global_load_lds_dwordx4 v165, s[24:25]
	s_waitcnt vmcnt(8)
	v_add_u32_e32 v154, s16, v225
	v_add_u32_e32 v155, s16, v226
	v_add_u32_e32 v156, s16, v227
	v_add_u32_e32 v157, s16, v228
	ds_read_b64_tr_b16 v[88:89], v154
	ds_read_b64_tr_b16 v[90:91], v155
	ds_read_b64_tr_b16 v[92:93], v156
	ds_read_b64_tr_b16 v[94:95], v157
	v_mfma_f32_16x16x16_bf16 v[96:99], v[202:203], v[4:5], v[96:99]
	v_mfma_f32_16x16x16_bf16 v[112:115], v[202:203], v[36:37], 0
	v_mfma_f32_16x16x16_bf16 v[100:103], v[204:205], v[4:5], v[100:103]
	v_mfma_f32_16x16x16_bf16 v[116:119], v[204:205], v[36:37], 0
	v_mfma_f32_16x16x16_bf16 v[104:107], v[206:207], v[4:5], v[104:107]
	v_mfma_f32_16x16x16_bf16 v[120:123], v[206:207], v[36:37], 0
	v_mfma_f32_16x16x16_bf16 v[108:111], v[208:209], v[4:5], v[108:111]
	v_mfma_f32_16x16x16_bf16 v[124:127], v[208:209], v[36:37], 0
	v_pk_add_f32 v[40:41], v[40:41], v[186:187] op_sel_hi:[1,0] neg_lo:[0,1] neg_hi:[0,1]
	v_pk_add_f32 v[42:43], v[42:43], v[186:187] op_sel_hi:[1,0] neg_lo:[0,1] neg_hi:[0,1]
	v_exp_f32_e32 v40, v40
	v_exp_f32_e32 v41, v41
	v_exp_f32_e32 v42, v42
	v_exp_f32_e32 v43, v43
	s_nop 0
	v_pk_add_f32 v[78:79], v[40:41], v[42:43]
	v_cvt_pk_bf16_f32 v40, v40, v41
	v_cvt_pk_bf16_f32 v41, v42, v43
	s_waitcnt lgkmcnt(0)
	s_add_i32 s93, s76, 48
	s_mov_b32 m0, s16
	v_add_u32_e32 v164, s93, v231
	v_med3_i32 v164, v164, 0, s40
	v_lshl_or_b32 v164, v164, 7, v222
	global_load_lds_dwordx4 v164, s[24:25]
	s_add_i32 m0, s16, 0x400
	v_add_u32_e32 v165, s93, v232
	v_med3_i32 v165, v165, 0, s40
	v_lshl_or_b32 v165, v165, 7, v222
	global_load_lds_dwordx4 v165, s[24:25]
	s_waitcnt vmcnt(8)
	v_add_u32_e32 v154, s12, v225
	v_add_u32_e32 v155, s12, v226
	v_add_u32_e32 v156, s12, v227
	v_add_u32_e32 v157, s12, v228
	ds_read_b64_tr_b16 v[202:203], v154
	ds_read_b64_tr_b16 v[204:205], v155
	ds_read_b64_tr_b16 v[206:207], v156
	ds_read_b64_tr_b16 v[208:209], v157
	v_mfma_f32_16x16x16_bf16 v[96:99], v[88:89], v[8:9], v[96:99]
	v_mfma_f32_16x16x16_bf16 v[112:115], v[88:89], v[40:41], v[112:115]
	v_mfma_f32_16x16x16_bf16 v[100:103], v[90:91], v[8:9], v[100:103]
	v_mfma_f32_16x16x16_bf16 v[116:119], v[90:91], v[40:41], v[116:119]
	v_mfma_f32_16x16x16_bf16 v[104:107], v[92:93], v[8:9], v[104:107]
	v_mfma_f32_16x16x16_bf16 v[120:123], v[92:93], v[40:41], v[120:123]
	v_mfma_f32_16x16x16_bf16 v[108:111], v[94:95], v[8:9], v[108:111]
	v_mfma_f32_16x16x16_bf16 v[124:127], v[94:95], v[40:41], v[124:127]
	v_pk_add_f32 v[44:45], v[44:45], v[186:187] op_sel_hi:[1,0] neg_lo:[0,1] neg_hi:[0,1]
	v_pk_add_f32 v[46:47], v[46:47], v[186:187] op_sel_hi:[1,0] neg_lo:[0,1] neg_hi:[0,1]
	v_exp_f32_e32 v44, v44
	v_exp_f32_e32 v45, v45
	v_exp_f32_e32 v46, v46
	v_exp_f32_e32 v47, v47
	s_nop 0
	v_pk_add_f32 v[76:77], v[76:77], v[44:45]
	v_pk_add_f32 v[78:79], v[78:79], v[46:47]
	v_cvt_pk_bf16_f32 v44, v44, v45
	v_cvt_pk_bf16_f32 v45, v46, v47
	s_waitcnt lgkmcnt(0)
	s_add_i32 s93, s76, 64
	s_mov_b32 m0, s12
	v_add_u32_e32 v164, s93, v231
	v_med3_i32 v164, v164, 0, s40
	v_lshl_or_b32 v164, v164, 7, v222
	global_load_lds_dwordx4 v164, s[24:25]
	s_add_i32 m0, s12, 0x400
	v_add_u32_e32 v165, s93, v232
	v_med3_i32 v165, v165, 0, s40
	v_lshl_or_b32 v165, v165, 7, v222
	global_load_lds_dwordx4 v165, s[24:25]
	s_waitcnt vmcnt(8)
	v_add_u32_e32 v154, s13, v225
	v_add_u32_e32 v155, s13, v226
	v_add_u32_e32 v156, s13, v227
	v_add_u32_e32 v157, s13, v228
	ds_read_b64_tr_b16 v[88:89], v154
	ds_read_b64_tr_b16 v[90:91], v155
	ds_read_b64_tr_b16 v[92:93], v156
	ds_read_b64_tr_b16 v[94:95], v157
	v_mfma_f32_16x16x16_bf16 v[96:99], v[202:203], v[12:13], v[96:99]
	v_mfma_f32_16x16x16_bf16 v[112:115], v[202:203], v[44:45], v[112:115]
	v_mfma_f32_16x16x16_bf16 v[100:103], v[204:205], v[12:13], v[100:103]
	v_mfma_f32_16x16x16_bf16 v[116:119], v[204:205], v[44:45], v[116:119]
	v_mfma_f32_16x16x16_bf16 v[104:107], v[206:207], v[12:13], v[104:107]
	v_mfma_f32_16x16x16_bf16 v[120:123], v[206:207], v[44:45], v[120:123]
	v_mfma_f32_16x16x16_bf16 v[108:111], v[208:209], v[12:13], v[108:111]
	v_mfma_f32_16x16x16_bf16 v[124:127], v[208:209], v[44:45], v[124:127]
	v_pk_add_f32 v[48:49], v[48:49], v[186:187] op_sel_hi:[1,0] neg_lo:[0,1] neg_hi:[0,1]
	v_pk_add_f32 v[50:51], v[50:51], v[186:187] op_sel_hi:[1,0] neg_lo:[0,1] neg_hi:[0,1]
	v_exp_f32_e32 v48, v48
	v_exp_f32_e32 v49, v49
	v_exp_f32_e32 v50, v50
	v_exp_f32_e32 v51, v51
	s_nop 0
	v_pk_add_f32 v[76:77], v[76:77], v[48:49]
	v_pk_add_f32 v[78:79], v[78:79], v[50:51]
	v_cvt_pk_bf16_f32 v48, v48, v49
	v_cvt_pk_bf16_f32 v49, v50, v51
	s_waitcnt lgkmcnt(0)
	s_add_i32 s93, s76, 0x50
	s_mov_b32 m0, s13
	v_add_u32_e32 v164, s93, v231
	v_med3_i32 v164, v164, 0, s40
	v_lshl_or_b32 v164, v164, 7, v222
	global_load_lds_dwordx4 v164, s[24:25]
	s_add_i32 m0, s13, 0x400
	v_add_u32_e32 v165, s93, v232
	v_med3_i32 v165, v165, 0, s40
	v_lshl_or_b32 v165, v165, 7, v222
	global_load_lds_dwordx4 v165, s[24:25]
	s_waitcnt vmcnt(8)
	v_add_u32_e32 v154, s14, v225
	v_add_u32_e32 v155, s14, v226
	v_add_u32_e32 v156, s14, v227
	v_add_u32_e32 v157, s14, v228
	ds_read_b64_tr_b16 v[202:203], v154
	ds_read_b64_tr_b16 v[204:205], v155
	ds_read_b64_tr_b16 v[206:207], v156
	ds_read_b64_tr_b16 v[208:209], v157
	v_mfma_f32_16x16x16_bf16 v[96:99], v[88:89], v[16:17], v[96:99]
	v_mfma_f32_16x16x16_bf16 v[112:115], v[88:89], v[48:49], v[112:115]
	v_mfma_f32_16x16x16_bf16 v[100:103], v[90:91], v[16:17], v[100:103]
	v_mfma_f32_16x16x16_bf16 v[116:119], v[90:91], v[48:49], v[116:119]
	v_mfma_f32_16x16x16_bf16 v[104:107], v[92:93], v[16:17], v[104:107]
	v_mfma_f32_16x16x16_bf16 v[120:123], v[92:93], v[48:49], v[120:123]
	v_mfma_f32_16x16x16_bf16 v[108:111], v[94:95], v[16:17], v[108:111]
	v_mfma_f32_16x16x16_bf16 v[124:127], v[94:95], v[48:49], v[124:127]
	v_pk_add_f32 v[52:53], v[52:53], v[186:187] op_sel_hi:[1,0] neg_lo:[0,1] neg_hi:[0,1]
	v_pk_add_f32 v[54:55], v[54:55], v[186:187] op_sel_hi:[1,0] neg_lo:[0,1] neg_hi:[0,1]
	v_exp_f32_e32 v52, v52
	v_exp_f32_e32 v53, v53
	v_exp_f32_e32 v54, v54
	v_exp_f32_e32 v55, v55
	s_nop 0
	v_pk_add_f32 v[76:77], v[76:77], v[52:53]
	v_pk_add_f32 v[78:79], v[78:79], v[54:55]
	v_cvt_pk_bf16_f32 v52, v52, v53
	v_cvt_pk_bf16_f32 v53, v54, v55
	s_waitcnt lgkmcnt(0)
	s_add_i32 s93, s79, 0
	s_mov_b32 m0, s14
	v_add_u32_e32 v164, s93, v162
	v_lshl_or_b32 v164, v164, 7, v220
	global_load_lds_dwordx4 v164, s[18:19]
	s_add_i32 m0, s14, 0x400
	v_add_u32_e32 v165, s93, v163
	v_lshl_or_b32 v165, v165, 7, v221
	global_load_lds_dwordx4 v165, s[18:19]
	s_waitcnt vmcnt(8)
	v_add_u32_e32 v154, s15, v225
	v_add_u32_e32 v155, s15, v226
	v_add_u32_e32 v156, s15, v227
	v_add_u32_e32 v157, s15, v228
	ds_read_b64_tr_b16 v[88:89], v154
	ds_read_b64_tr_b16 v[90:91], v155
	ds_read_b64_tr_b16 v[92:93], v156
	ds_read_b64_tr_b16 v[94:95], v157
	v_mfma_f32_16x16x16_bf16 v[96:99], v[202:203], v[20:21], v[96:99]
	v_mfma_f32_16x16x16_bf16 v[112:115], v[202:203], v[52:53], v[112:115]
	v_mfma_f32_16x16x16_bf16 v[100:103], v[204:205], v[20:21], v[100:103]
	v_mfma_f32_16x16x16_bf16 v[116:119], v[204:205], v[52:53], v[116:119]
	v_mfma_f32_16x16x16_bf16 v[104:107], v[206:207], v[20:21], v[104:107]
	v_mfma_f32_16x16x16_bf16 v[120:123], v[206:207], v[52:53], v[120:123]
	v_mfma_f32_16x16x16_bf16 v[108:111], v[208:209], v[20:21], v[108:111]
	v_mfma_f32_16x16x16_bf16 v[124:127], v[208:209], v[52:53], v[124:127]
	v_pk_add_f32 v[56:57], v[56:57], v[186:187] op_sel_hi:[1,0] neg_lo:[0,1] neg_hi:[0,1]
	v_pk_add_f32 v[58:59], v[58:59], v[186:187] op_sel_hi:[1,0] neg_lo:[0,1] neg_hi:[0,1]
	v_exp_f32_e32 v56, v56
	v_exp_f32_e32 v57, v57
	v_exp_f32_e32 v58, v58
	v_exp_f32_e32 v59, v59
	s_nop 0
	v_pk_add_f32 v[76:77], v[76:77], v[56:57]
	v_pk_add_f32 v[78:79], v[78:79], v[58:59]
	v_cvt_pk_bf16_f32 v56, v56, v57
	v_cvt_pk_bf16_f32 v57, v58, v59
	s_waitcnt lgkmcnt(0)
	s_add_i32 s93, s79, 64
	s_mov_b32 m0, s15
	v_add_u32_e32 v164, s93, v162
	v_lshl_or_b32 v164, v164, 7, v220
	global_load_lds_dwordx4 v164, s[18:19]
	s_add_i32 m0, s15, 0x400
	v_add_u32_e32 v165, s93, v163
	v_lshl_or_b32 v165, v165, 7, v221
	global_load_lds_dwordx4 v165, s[18:19]
	s_waitcnt vmcnt(8)
	v_add_u32_e32 v154, s16, v225
	v_add_u32_e32 v155, s16, v226
	v_add_u32_e32 v156, s16, v227
	v_add_u32_e32 v157, s16, v228
	ds_read_b64_tr_b16 v[202:203], v154
	ds_read_b64_tr_b16 v[204:205], v155
	ds_read_b64_tr_b16 v[206:207], v156
	ds_read_b64_tr_b16 v[208:209], v157
	v_mfma_f32_16x16x16_bf16 v[96:99], v[88:89], v[24:25], v[96:99]
	v_mfma_f32_16x16x16_bf16 v[112:115], v[88:89], v[56:57], v[112:115]
	v_mfma_f32_16x16x16_bf16 v[100:103], v[90:91], v[24:25], v[100:103]
	v_mfma_f32_16x16x16_bf16 v[116:119], v[90:91], v[56:57], v[116:119]
	v_mfma_f32_16x16x16_bf16 v[104:107], v[92:93], v[24:25], v[104:107]
	v_mfma_f32_16x16x16_bf16 v[120:123], v[92:93], v[56:57], v[120:123]
	v_mfma_f32_16x16x16_bf16 v[108:111], v[94:95], v[24:25], v[108:111]
	v_mfma_f32_16x16x16_bf16 v[124:127], v[94:95], v[56:57], v[124:127]
	v_pk_add_f32 v[60:61], v[60:61], v[186:187] op_sel_hi:[1,0] neg_lo:[0,1] neg_hi:[0,1]
	v_pk_add_f32 v[62:63], v[62:63], v[186:187] op_sel_hi:[1,0] neg_lo:[0,1] neg_hi:[0,1]
	v_exp_f32_e32 v60, v60
	v_exp_f32_e32 v61, v61
	v_exp_f32_e32 v62, v62
	v_exp_f32_e32 v63, v63
	s_nop 0
	v_pk_add_f32 v[76:77], v[76:77], v[60:61]
	v_pk_add_f32 v[78:79], v[78:79], v[62:63]
	v_cvt_pk_bf16_f32 v60, v60, v61
	v_cvt_pk_bf16_f32 v61, v62, v63
	s_waitcnt lgkmcnt(0)
	s_add_i32 s93, s79, 0xffffff00
	s_mov_b32 m0, s16
	v_add_u32_e32 v164, s93, v162
	v_med3_i32 v164, v164, 0, s40
	v_lshl_or_b32 v164, v164, 7, v220
	global_load_lds_dwordx4 v164, s[20:21]
	s_add_i32 m0, s16, 0x400
	v_add_u32_e32 v165, s93, v163
	v_med3_i32 v165, v165, 0, s40
	v_lshl_or_b32 v165, v165, 7, v221
	global_load_lds_dwordx4 v165, s[20:21]
	s_waitcnt vmcnt(8)
	v_add_u32_e32 v154, s12, v225
	v_add_u32_e32 v155, s12, v226
	v_add_u32_e32 v156, s12, v227
	v_add_u32_e32 v157, s12, v228
	ds_read_b64_tr_b16 v[88:89], v154
	ds_read_b64_tr_b16 v[90:91], v155
	ds_read_b64_tr_b16 v[92:93], v156
	ds_read_b64_tr_b16 v[94:95], v157
	v_mfma_f32_16x16x16_bf16 v[96:99], v[202:203], v[28:29], v[96:99]
	v_mfma_f32_16x16x16_bf16 v[112:115], v[202:203], v[60:61], v[112:115]
	v_mfma_f32_16x16x16_bf16 v[100:103], v[204:205], v[28:29], v[100:103]
	v_mfma_f32_16x16x16_bf16 v[116:119], v[204:205], v[60:61], v[116:119]
	v_mfma_f32_16x16x16_bf16 v[104:107], v[206:207], v[28:29], v[104:107]
	v_mfma_f32_16x16x16_bf16 v[120:123], v[206:207], v[60:61], v[120:123]
	v_mfma_f32_16x16x16_bf16 v[108:111], v[208:209], v[28:29], v[108:111]
	v_mfma_f32_16x16x16_bf16 v[124:127], v[208:209], v[60:61], v[124:127]
	v_pk_add_f32 v[64:65], v[64:65], v[186:187] op_sel_hi:[1,0] neg_lo:[0,1] neg_hi:[0,1]
	v_pk_add_f32 v[66:67], v[66:67], v[186:187] op_sel_hi:[1,0] neg_lo:[0,1] neg_hi:[0,1]
	v_exp_f32_e32 v64, v64
	v_exp_f32_e32 v65, v65
	v_exp_f32_e32 v66, v66
	v_exp_f32_e32 v67, v67
	s_nop 0
	v_pk_add_f32 v[76:77], v[76:77], v[64:65]
	v_pk_add_f32 v[78:79], v[78:79], v[66:67]
	v_cvt_pk_bf16_f32 v64, v64, v65
	v_cvt_pk_bf16_f32 v65, v66, v67
	s_waitcnt lgkmcnt(0)
	s_add_i32 s93, s79, 0xffffff40
	s_mov_b32 m0, s12
	v_add_u32_e32 v164, s93, v162
	v_med3_i32 v164, v164, 0, s40
	v_lshl_or_b32 v164, v164, 7, v220
	global_load_lds_dwordx4 v164, s[20:21]
	s_add_i32 m0, s12, 0x400
	v_add_u32_e32 v165, s93, v163
	v_med3_i32 v165, v165, 0, s40
	v_lshl_or_b32 v165, v165, 7, v221
	global_load_lds_dwordx4 v165, s[20:21]
	s_waitcnt vmcnt(8)
	v_add_u32_e32 v154, s13, v225
	v_add_u32_e32 v155, s13, v226
	v_add_u32_e32 v156, s13, v227
	v_add_u32_e32 v157, s13, v228
	ds_read_b64_tr_b16 v[202:203], v154
	ds_read_b64_tr_b16 v[204:205], v155
	ds_read_b64_tr_b16 v[206:207], v156
	ds_read_b64_tr_b16 v[208:209], v157
	v_mfma_f32_16x16x16_bf16 v[96:99], v[88:89], v[32:33], v[96:99]
	v_mfma_f32_16x16x16_bf16 v[112:115], v[88:89], v[64:65], v[112:115]
	v_mfma_f32_16x16x16_bf16 v[100:103], v[90:91], v[32:33], v[100:103]
	v_mfma_f32_16x16x16_bf16 v[116:119], v[90:91], v[64:65], v[116:119]
	v_mfma_f32_16x16x16_bf16 v[104:107], v[92:93], v[32:33], v[104:107]
	v_mfma_f32_16x16x16_bf16 v[120:123], v[92:93], v[64:65], v[120:123]
	v_mfma_f32_16x16x16_bf16 v[108:111], v[94:95], v[32:33], v[108:111]
	v_mfma_f32_16x16x16_bf16 v[124:127], v[94:95], v[64:65], v[124:127]
	v_pk_add_f32 v[68:69], v[68:69], v[186:187] op_sel_hi:[1,0] neg_lo:[0,1] neg_hi:[0,1]
	v_pk_add_f32 v[70:71], v[70:71], v[186:187] op_sel_hi:[1,0] neg_lo:[0,1] neg_hi:[0,1]
	v_exp_f32_e32 v68, v68
	v_exp_f32_e32 v69, v69
	v_exp_f32_e32 v70, v70
	v_exp_f32_e32 v71, v71
	s_nop 0
	v_pk_add_f32 v[76:77], v[76:77], v[68:69]
	v_pk_add_f32 v[78:79], v[78:79], v[70:71]
	v_cvt_pk_bf16_f32 v68, v68, v69
	v_cvt_pk_bf16_f32 v69, v70, v71
	s_waitcnt lgkmcnt(0)
	s_add_i32 s93, s79, 0xffffff80
	s_mov_b32 m0, s13
	v_add_u32_e32 v164, s93, v162
	v_med3_i32 v164, v164, 0, s40
	v_lshl_or_b32 v164, v164, 7, v220
	global_load_lds_dwordx4 v164, s[20:21]
	s_add_i32 m0, s13, 0x400
	v_add_u32_e32 v165, s93, v163
	v_med3_i32 v165, v165, 0, s40
	v_lshl_or_b32 v165, v165, 7, v221
	global_load_lds_dwordx4 v165, s[20:21]
	v_mfma_f32_16x16x16_bf16 v[112:115], v[202:203], v[68:69], v[112:115]
	v_mfma_f32_16x16x16_bf16 v[116:119], v[204:205], v[68:69], v[116:119]
	v_mfma_f32_16x16x16_bf16 v[120:123], v[206:207], v[68:69], v[120:123]
	v_mfma_f32_16x16x16_bf16 v[124:127], v[208:209], v[68:69], v[124:127]
	s_nop 0
	v_pk_add_f32 v[76:77], v[76:77], v[78:79]
	s_nop 0
	v_add_f32_e32 v187, v76, v77
	v_mov_b32_e32 v146, v187
	s_nop 1
	v_permlane16_swap_b32_e32 v187, v146
	v_add_f32_e32 v187, v187, v146
	v_mov_b32_e32 v146, v187
	s_nop 1
	v_permlane32_swap_b32_e32 v187, v146
	v_add_f32_e32 v187, v187, v146
	s_and_saveexec_b64 s[80:81], s[74:75]
	ds_write_b64 v194, v[184:185]
	s_mov_b64 exec, s[80:81]
	ds_write_b128 v190, v[96:99]
	ds_write_b128 v191, v[100:103]
	ds_write_b128 v192, v[104:107]
	ds_write_b128 v193, v[108:111]
	s_and_saveexec_b64 s[80:81], s[74:75]
	ds_write_b64 v199, v[186:187]
	s_mov_b64 exec, s[80:81]
	ds_write_b128 v195, v[112:115]
	ds_write_b128 v196, v[116:119]
	ds_write_b128 v197, v[120:123]
	ds_write_b128 v198, v[124:127]
	s_waitcnt lgkmcnt(0)
	s_barrier
	s_add_i32 s76, s38, s83
	s_add_i32 s79, s38, s84
	v_lshlrev_b32_e32 v231, 2, v218
	v_add_u32_e32 v232, 8, v218
	v_lshlrev_b32_e32 v232, 2, v232
	v_lshlrev_b32_e32 v162, 4, v218
	v_add_u32_e32 v163, 8, v218
	v_lshlrev_b32_e32 v163, 4, v163
	s_waitcnt vmcnt(8)
	v_add_u32_e32 v154, s14, v223
	v_add_u32_e32 v155, s14, v224
	ds_read_b128 v[72:75], v154
	ds_read_b128 v[76:79], v155
	s_waitcnt lgkmcnt(0)
	s_add_i32 s93, s76, 0xffffffc0
	s_mov_b32 m0, s14
	v_add_u32_e32 v164, s93, v231
	v_med3_i32 v164, v164, 0, s40
	v_lshl_or_b32 v164, v164, 7, v220
	global_load_lds_dwordx4 v164, s[20:21]
	s_add_i32 m0, s14, 0x400
	v_add_u32_e32 v165, s93, v232
	v_med3_i32 v165, v165, 0, s40
	v_lshl_or_b32 v165, v165, 7, v221
	global_load_lds_dwordx4 v165, s[20:21]
	s_waitcnt vmcnt(8)
	v_add_u32_e32 v154, s15, v223
	v_add_u32_e32 v155, s15, v224
	ds_read_b128 v[80:83], v154
	ds_read_b128 v[84:87], v155
	s_waitcnt lgkmcnt(0)
	s_add_i32 s93, s76, 0
	s_mov_b32 m0, s15
	v_add_u32_e32 v164, s93, v231
	v_med3_i32 v164, v164, 0, s40
	v_lshl_or_b32 v164, v164, 7, v220
	global_load_lds_dwordx4 v164, s[20:21]
	s_add_i32 m0, s15, 0x400
	v_add_u32_e32 v165, s93, v232
	v_med3_i32 v165, v165, 0, s40
	v_lshl_or_b32 v165, v165, 7, v221
	global_load_lds_dwordx4 v165, s[20:21]
	s_waitcnt vmcnt(8)
	v_add_u32_e32 v154, s16, v223
	v_add_u32_e32 v155, s16, v224
	ds_read_b128 v[88:91], v154
	ds_read_b128 v[92:95], v155
	s_waitcnt lgkmcnt(0)
	s_add_i32 s93, s76, 64
	s_mov_b32 m0, s16
	v_add_u32_e32 v164, s93, v231
	v_med3_i32 v164, v164, 0, s40
	v_lshl_or_b32 v164, v164, 7, v220
	global_load_lds_dwordx4 v164, s[20:21]
	s_add_i32 m0, s16, 0x400
	v_add_u32_e32 v165, s93, v232
	v_med3_i32 v165, v165, 0, s40
	v_lshl_or_b32 v165, v165, 7, v221
	global_load_lds_dwordx4 v165, s[20:21]
	s_waitcnt vmcnt(8)
	v_add_u32_e32 v154, s12, v223
	v_add_u32_e32 v155, s12, v224
	ds_read_b128 v[202:205], v154
	ds_read_b128 v[206:209], v155
	v_mfma_f32_16x16x32_bf16 v[0:3], v[88:91], v[72:75], 0
	v_mfma_f32_16x16x32_bf16 v[0:3], v[92:95], v[76:79], v[0:3]
	s_waitcnt lgkmcnt(0)
	s_add_i32 s93, s76, 0x80
	s_mov_b32 m0, s12
	v_add_u32_e32 v164, s93, v231
	v_med3_i32 v164, v164, 0, s40
	v_lshl_or_b32 v164, v164, 7, v220
	global_load_lds_dwordx4 v164, s[20:21]
	s_add_i32 m0, s12, 0x400
	v_add_u32_e32 v165, s93, v232
	v_med3_i32 v165, v165, 0, s40
	v_lshl_or_b32 v165, v165, 7, v221
	global_load_lds_dwordx4 v165, s[20:21]
	s_waitcnt vmcnt(8)
	v_add_u32_e32 v154, s13, v223
	v_add_u32_e32 v155, s13, v224
	ds_read_b128 v[88:91], v154
	ds_read_b128 v[92:95], v155
	v_mfma_f32_16x16x32_bf16 v[4:7], v[202:205], v[72:75], 0
	v_mfma_f32_16x16x32_bf16 v[36:39], v[202:205], v[80:83], 0
	v_mfma_f32_16x16x32_bf16 v[4:7], v[206:209], v[76:79], v[4:7]
	v_mfma_f32_16x16x32_bf16 v[36:39], v[206:209], v[84:87], v[36:39]
	s_waitcnt lgkmcnt(0)
	s_add_i32 s93, s76, 0xc0
	s_mov_b32 m0, s13
	v_add_u32_e32 v164, s93, v231
	v_med3_i32 v164, v164, 0, s40
	v_lshl_or_b32 v164, v164, 7, v220
	global_load_lds_dwordx4 v164, s[20:21]
	s_add_i32 m0, s13, 0x400
	v_add_u32_e32 v165, s93, v232
	v_med3_i32 v165, v165, 0, s40
	v_lshl_or_b32 v165, v165, 7, v221
	global_load_lds_dwordx4 v165, s[20:21]
	s_waitcnt vmcnt(8)
	v_add_u32_e32 v154, s14, v223
	v_add_u32_e32 v155, s14, v224
	ds_read_b128 v[202:205], v154
	ds_read_b128 v[206:209], v155
	v_mfma_f32_16x16x32_bf16 v[8:11], v[88:91], v[72:75], 0
	v_mfma_f32_16x16x32_bf16 v[40:43], v[88:91], v[80:83], 0
	v_mfma_f32_16x16x32_bf16 v[8:11], v[92:95], v[76:79], v[8:11]
	v_mfma_f32_16x16x32_bf16 v[40:43], v[92:95], v[84:87], v[40:43]
	v_mov_b32_e32 v188, s83
	v_lshl_add_u32 v188, v216, 2, v188
	v_lshrrev_b32_e32 v146, 4, v188
	v_xor_b32_e32 v146, v146, v188
	v_and_b32_e32 v146, 15, v146
	v_lshlrev_b32_e32 v147, 8, v188
	v_or_b32_e32 v148, 0, v217
	s_waitcnt lgkmcnt(0)
	s_add_i32 s93, s76, 0x100
	s_mov_b32 m0, s14
	v_add_u32_e32 v164, s93, v231
	v_med3_i32 v164, v164, 0, s40
	v_lshl_or_b32 v164, v164, 7, v220
	global_load_lds_dwordx4 v164, s[20:21]
	s_add_i32 m0, s14, 0x400
	v_add_u32_e32 v165, s93, v232
	v_med3_i32 v165, v165, 0, s40
	v_lshl_or_b32 v165, v165, 7, v221
	global_load_lds_dwordx4 v165, s[20:21]
	s_waitcnt vmcnt(8)
	v_add_u32_e32 v154, s15, v223
	v_add_u32_e32 v155, s15, v224
	ds_read_b128 v[88:91], v154
	ds_read_b128 v[92:95], v155
	v_mfma_f32_16x16x32_bf16 v[12:15], v[202:205], v[72:75], 0
	v_mfma_f32_16x16x32_bf16 v[44:47], v[202:205], v[80:83], 0
	v_mfma_f32_16x16x32_bf16 v[12:15], v[206:209], v[76:79], v[12:15]
	v_mfma_f32_16x16x32_bf16 v[44:47], v[206:209], v[84:87], v[44:47]
	v_xor_b32_e32 v148, v148, v146
	v_lshl_add_u32 v190, v148, 4, v147
	v_or_b32_e32 v148, 4, v217
	v_xor_b32_e32 v148, v148, v146
	v_lshl_add_u32 v191, v148, 4, v147
	v_or_b32_e32 v148, 8, v217
	v_xor_b32_e32 v148, v148, v146
	s_waitcnt lgkmcnt(0)
	s_add_i32 s93, s76, 0x140
	s_mov_b32 m0, s15
	v_add_u32_e32 v164, s93, v231
	v_med3_i32 v164, v164, 0, s40
	v_lshl_or_b32 v164, v164, 7, v220
	global_load_lds_dwordx4 v164, s[20:21]
	s_add_i32 m0, s15, 0x400
	v_add_u32_e32 v165, s93, v232
	v_med3_i32 v165, v165, 0, s40
	v_lshl_or_b32 v165, v165, 7, v221
	global_load_lds_dwordx4 v165, s[20:21]
	s_waitcnt vmcnt(8)
	v_add_u32_e32 v154, s16, v223
	v_add_u32_e32 v155, s16, v224
	ds_read_b128 v[202:205], v154
	ds_read_b128 v[206:209], v155
	v_mfma_f32_16x16x32_bf16 v[16:19], v[88:91], v[72:75], 0
	v_mfma_f32_16x16x32_bf16 v[48:51], v[88:91], v[80:83], 0
	v_mfma_f32_16x16x32_bf16 v[16:19], v[92:95], v[76:79], v[16:19]
	v_mfma_f32_16x16x32_bf16 v[48:51], v[92:95], v[84:87], v[48:51]
	v_lshl_add_u32 v192, v148, 4, v147
	v_or_b32_e32 v148, 12, v217
	v_xor_b32_e32 v148, v148, v146
	v_lshl_add_u32 v193, v148, 4, v147
	v_lshlrev_b32_e32 v194, 3, v188
	v_add_u32_e32 v194, 0x10000, v194
	ds_read_b64 v[144:145], v194
	s_waitcnt lgkmcnt(0)
	s_add_i32 s93, s76, 0xffffff00
	s_mov_b32 m0, s16
	v_add_u32_e32 v164, s93, v231
	v_med3_i32 v164, v164, 0, s40
	v_lshl_or_b32 v164, v164, 7, v222
	global_load_lds_dwordx4 v164, s[24:25]
	s_add_i32 m0, s16, 0x400
	v_add_u32_e32 v165, s93, v232
	v_med3_i32 v165, v165, 0, s40
	v_lshl_or_b32 v165, v165, 7, v222
	global_load_lds_dwordx4 v165, s[24:25]
	s_waitcnt vmcnt(8)
	v_add_u32_e32 v154, s12, v223
	v_add_u32_e32 v155, s12, v224
	ds_read_b128 v[88:91], v154
	ds_read_b128 v[92:95], v155
	v_mfma_f32_16x16x32_bf16 v[20:23], v[202:205], v[72:75], 0
	v_mfma_f32_16x16x32_bf16 v[52:55], v[202:205], v[80:83], 0
	v_mfma_f32_16x16x32_bf16 v[20:23], v[206:209], v[76:79], v[20:23]
	v_mfma_f32_16x16x32_bf16 v[52:55], v[206:209], v[84:87], v[52:55]
	ds_read_b128 v[128:131], v190
	ds_read_b128 v[132:135], v191
	ds_read_b128 v[136:139], v192
	ds_read_b128 v[140:143], v193
	v_mov_b32_e32 v189, s83
	v_lshl_add_u32 v189, v216, 2, v189
	v_add_u32_e32 v189, 64, v189
	s_waitcnt lgkmcnt(0)
	s_add_i32 s93, s76, 0xffffff40
	s_mov_b32 m0, s12
	v_add_u32_e32 v164, s93, v231
	v_med3_i32 v164, v164, 0, s40
	v_lshl_or_b32 v164, v164, 7, v222
	global_load_lds_dwordx4 v164, s[24:25]
	s_add_i32 m0, s12, 0x400
	v_add_u32_e32 v165, s93, v232
	v_med3_i32 v165, v165, 0, s40
	v_lshl_or_b32 v165, v165, 7, v222
	global_load_lds_dwordx4 v165, s[24:25]
	s_waitcnt vmcnt(8)
	v_add_u32_e32 v154, s13, v223
	v_add_u32_e32 v155, s13, v224
	ds_read_b128 v[202:205], v154
	ds_read_b128 v[206:209], v155
	v_mfma_f32_16x16x32_bf16 v[24:27], v[88:91], v[72:75], 0
	v_mfma_f32_16x16x32_bf16 v[56:59], v[88:91], v[80:83], 0
	v_mfma_f32_16x16x32_bf16 v[24:27], v[92:95], v[76:79], v[24:27]
	v_mfma_f32_16x16x32_bf16 v[56:59], v[92:95], v[84:87], v[56:59]
	v_lshrrev_b32_e32 v146, 4, v189
	v_xor_b32_e32 v146, v146, v189
	v_and_b32_e32 v146, 15, v146
	v_lshlrev_b32_e32 v147, 8, v189
	v_or_b32_e32 v148, 0, v217
	v_xor_b32_e32 v148, v148, v146
	v_lshl_add_u32 v195, v148, 4, v147
	s_waitcnt lgkmcnt(0)
	s_add_i32 s93, s76, 0xffffff80
	s_mov_b32 m0, s13
	v_add_u32_e32 v164, s93, v231
	v_med3_i32 v164, v164, 0, s40
	v_lshl_or_b32 v164, v164, 7, v222
	global_load_lds_dwordx4 v164, s[24:25]
	s_add_i32 m0, s13, 0x400
	v_add_u32_e32 v165, s93, v232
	v_med3_i32 v165, v165, 0, s40
	v_lshl_or_b32 v165, v165, 7, v222
	global_load_lds_dwordx4 v165, s[24:25]
	s_waitcnt vmcnt(8)
	v_add_u32_e32 v154, s14, v223
	v_add_u32_e32 v155, s14, v224
	ds_read_b128 v[88:91], v154
	ds_read_b128 v[92:95], v155
	v_mfma_f32_16x16x32_bf16 v[28:31], v[202:205], v[72:75], 0
	v_mfma_f32_16x16x32_bf16 v[60:63], v[202:205], v[80:83], 0
	v_mfma_f32_16x16x32_bf16 v[28:31], v[206:209], v[76:79], v[28:31]
	v_mfma_f32_16x16x32_bf16 v[60:63], v[206:209], v[84:87], v[60:63]
	v_or_b32_e32 v148, 4, v217
	v_xor_b32_e32 v148, v148, v146
	v_lshl_add_u32 v196, v148, 4, v147
	v_or_b32_e32 v148, 8, v217
	v_xor_b32_e32 v148, v148, v146
	v_lshl_add_u32 v197, v148, 4, v147
	v_or_b32_e32 v148, 12, v217
	s_waitcnt lgkmcnt(0)
	s_add_i32 s93, s76, 0xffffffc0
	s_mov_b32 m0, s14
	v_add_u32_e32 v164, s93, v231
	v_med3_i32 v164, v164, 0, s40
	v_lshl_or_b32 v164, v164, 7, v222
	global_load_lds_dwordx4 v164, s[24:25]
	s_add_i32 m0, s14, 0x400
	v_add_u32_e32 v165, s93, v232
	v_med3_i32 v165, v165, 0, s40
	v_lshl_or_b32 v165, v165, 7, v222
	global_load_lds_dwordx4 v165, s[24:25]
	s_waitcnt vmcnt(8)
	v_add_u32_e32 v154, s15, v223
	v_add_u32_e32 v155, s15, v224
	ds_read_b128 v[202:205], v154
	ds_read_b128 v[206:209], v155
	v_mfma_f32_16x16x32_bf16 v[32:35], v[88:91], v[72:75], 0
	v_mfma_f32_16x16x32_bf16 v[64:67], v[88:91], v[80:83], 0
	v_mfma_f32_16x16x32_bf16 v[32:35], v[92:95], v[76:79], v[32:35]
	v_mfma_f32_16x16x32_bf16 v[64:67], v[92:95], v[84:87], v[64:67]
	v_xor_b32_e32 v148, v148, v146
	v_lshl_add_u32 v198, v148, 4, v147
	v_lshlrev_b32_e32 v199, 3, v189
	v_add_u32_e32 v199, 0x10000, v199
	ds_read_b64 v[182:183], v199
	ds_read_b128 v[166:169], v195
	ds_read_b128 v[170:173], v196
	s_waitcnt lgkmcnt(0)
	s_add_i32 s93, s76, 0
	s_mov_b32 m0, s15
	v_add_u32_e32 v164, s93, v231
	v_med3_i32 v164, v164, 0, s40
	v_lshl_or_b32 v164, v164, 7, v222
	global_load_lds_dwordx4 v164, s[24:25]
	s_add_i32 m0, s15, 0x400
	v_add_u32_e32 v165, s93, v232
	v_med3_i32 v165, v165, 0, s40
	v_lshl_or_b32 v165, v165, 7, v222
	global_load_lds_dwordx4 v165, s[24:25]
	s_waitcnt vmcnt(8)
	v_add_u32_e32 v154, s16, v225
	v_add_u32_e32 v155, s16, v226
	v_add_u32_e32 v156, s16, v227
	v_add_u32_e32 v157, s16, v228
	ds_read_b64_tr_b16 v[88:89], v154
	ds_read_b64_tr_b16 v[90:91], v155
	ds_read_b64_tr_b16 v[92:93], v156
	ds_read_b64_tr_b16 v[94:95], v157
	v_mfma_f32_16x16x32_bf16 v[68:71], v[202:205], v[80:83], 0
	v_mfma_f32_16x16x32_bf16 v[68:71], v[206:209], v[84:87], v[68:71]
	ds_read_b128 v[174:177], v197
	ds_read_b128 v[178:181], v198
	s_add_i32 s90, s76, 0x17c
	s_cmp_gt_i32 s90, s40
	s_cselect_b32 s96, 1, 0
	s_cmp_lt_i32 s76, 0x100
	s_cselect_b32 s96, 1, s96
	s_ashr_i32 s77, s76, 2
	s_sub_i32 s77, 64, s77
	s_sub_i32 s78, s40, s76
	s_ashr_i32 s78, s78, 2
	s_add_i32 s78, s78, 64
	v_cndmask_b32_e64 v0, v0, v230, s[52:53]
	v_cndmask_b32_e64 v32, v32, v230, s[62:63]
	v_cndmask_b32_e64 v1, v1, v230, s[56:57]
	v_cndmask_b32_e64 v33, v33, v230, s[64:65]
	v_cndmask_b32_e64 v2, v2, v230, s[58:59]
	v_cndmask_b32_e64 v34, v34, v230, s[70:71]
	v_cndmask_b32_e64 v3, v3, v230, s[60:61]
	v_cndmask_b32_e64 v35, v35, v230, s[72:73]
	s_cmp_eq_u32 s96, 0
	s_cbranch_scc1 .Latt_noedge_3
	v_sub_u32_e32 v200, s77, v229
	s_sub_i32 s91, s78, s77
	v_sub_u32_e32 v150, 0, v200
	v_sub_u32_e32 v151, 1, v200
	v_sub_u32_e32 v152, 2, v200
	v_sub_u32_e32 v153, 3, v200
	v_cmp_lt_u32_e64 s[94:95], s91, v150
	v_cmp_lt_u32_e64 s[86:87], s91, v151
	v_cmp_lt_u32_e64 s[0:1], s91, v152
	v_cmp_lt_u32_e64 s[2:3], s91, v153
	v_cndmask_b32_e64 v0, v0, v230, s[94:95]
	v_cndmask_b32_e64 v1, v1, v230, s[86:87]
	v_cndmask_b32_e64 v2, v2, v230, s[0:1]
	v_cndmask_b32_e64 v3, v3, v230, s[2:3]
	v_sub_u32_e32 v150, 16, v200
	v_sub_u32_e32 v151, 17, v200
	v_sub_u32_e32 v152, 18, v200
	v_sub_u32_e32 v153, 19, v200
	v_cmp_lt_u32_e64 s[94:95], s91, v150
	v_cmp_lt_u32_e64 s[86:87], s91, v151
	v_cmp_lt_u32_e64 s[0:1], s91, v152
	v_cmp_lt_u32_e64 s[2:3], s91, v153
	v_cndmask_b32_e64 v4, v4, v230, s[94:95]
	v_cndmask_b32_e64 v5, v5, v230, s[86:87]
	v_cndmask_b32_e64 v6, v6, v230, s[0:1]
	v_cndmask_b32_e64 v7, v7, v230, s[2:3]
	v_sub_u32_e32 v150, 32, v200
	v_sub_u32_e32 v151, 33, v200
	v_sub_u32_e32 v152, 34, v200
	v_sub_u32_e32 v153, 35, v200
	v_cmp_lt_u32_e64 s[94:95], s91, v150
	v_cmp_lt_u32_e64 s[86:87], s91, v151
	v_cmp_lt_u32_e64 s[0:1], s91, v152
	v_cmp_lt_u32_e64 s[2:3], s91, v153
	v_cndmask_b32_e64 v8, v8, v230, s[94:95]
	v_cndmask_b32_e64 v9, v9, v230, s[86:87]
	v_cndmask_b32_e64 v10, v10, v230, s[0:1]
	v_cndmask_b32_e64 v11, v11, v230, s[2:3]
	v_sub_u32_e32 v150, 48, v200
	v_sub_u32_e32 v151, 49, v200
	v_sub_u32_e32 v152, 50, v200
	v_sub_u32_e32 v153, 51, v200
	v_cmp_lt_u32_e64 s[94:95], s91, v150
	v_cmp_lt_u32_e64 s[86:87], s91, v151
	v_cmp_lt_u32_e64 s[0:1], s91, v152
	v_cmp_lt_u32_e64 s[2:3], s91, v153
	v_cndmask_b32_e64 v12, v12, v230, s[94:95]
	v_cndmask_b32_e64 v13, v13, v230, s[86:87]
	v_cndmask_b32_e64 v14, v14, v230, s[0:1]
	v_cndmask_b32_e64 v15, v15, v230, s[2:3]
	v_sub_u32_e32 v150, 64, v200
	v_sub_u32_e32 v151, 0x41, v200
	v_sub_u32_e32 v152, 0x42, v200
	v_sub_u32_e32 v153, 0x43, v200
	v_cmp_lt_u32_e64 s[94:95], s91, v150
	v_cmp_lt_u32_e64 s[86:87], s91, v151
	v_cmp_lt_u32_e64 s[0:1], s91, v152
	v_cmp_lt_u32_e64 s[2:3], s91, v153
	v_cndmask_b32_e64 v16, v16, v230, s[94:95]
	v_cndmask_b32_e64 v17, v17, v230, s[86:87]
	v_cndmask_b32_e64 v18, v18, v230, s[0:1]
	v_cndmask_b32_e64 v19, v19, v230, s[2:3]
	v_sub_u32_e32 v150, 0x50, v200
	v_sub_u32_e32 v151, 0x51, v200
	v_sub_u32_e32 v152, 0x52, v200
	v_sub_u32_e32 v153, 0x53, v200
	v_cmp_lt_u32_e64 s[94:95], s91, v150
	v_cmp_lt_u32_e64 s[86:87], s91, v151
	v_cmp_lt_u32_e64 s[0:1], s91, v152
	v_cmp_lt_u32_e64 s[2:3], s91, v153
	v_cndmask_b32_e64 v20, v20, v230, s[94:95]
	v_cndmask_b32_e64 v21, v21, v230, s[86:87]
	v_cndmask_b32_e64 v22, v22, v230, s[0:1]
	v_cndmask_b32_e64 v23, v23, v230, s[2:3]
	v_sub_u32_e32 v150, 0x60, v200
	v_sub_u32_e32 v151, 0x61, v200
	v_sub_u32_e32 v152, 0x62, v200
	v_sub_u32_e32 v153, 0x63, v200
	v_cmp_lt_u32_e64 s[94:95], s91, v150
	v_cmp_lt_u32_e64 s[86:87], s91, v151
	v_cmp_lt_u32_e64 s[0:1], s91, v152
	v_cmp_lt_u32_e64 s[2:3], s91, v153
	v_cndmask_b32_e64 v24, v24, v230, s[94:95]
	v_cndmask_b32_e64 v25, v25, v230, s[86:87]
	v_cndmask_b32_e64 v26, v26, v230, s[0:1]
	v_cndmask_b32_e64 v27, v27, v230, s[2:3]
	v_sub_u32_e32 v150, 0x70, v200
	v_sub_u32_e32 v151, 0x71, v200
	v_sub_u32_e32 v152, 0x72, v200
	v_sub_u32_e32 v153, 0x73, v200
	v_cmp_lt_u32_e64 s[94:95], s91, v150
	v_cmp_lt_u32_e64 s[86:87], s91, v151
	v_cmp_lt_u32_e64 s[0:1], s91, v152
	v_cmp_lt_u32_e64 s[2:3], s91, v153
	v_cndmask_b32_e64 v28, v28, v230, s[94:95]
	v_cndmask_b32_e64 v29, v29, v230, s[86:87]
	v_cndmask_b32_e64 v30, v30, v230, s[0:1]
	v_cndmask_b32_e64 v31, v31, v230, s[2:3]
	v_sub_u32_e32 v150, 0x80, v200
	v_sub_u32_e32 v151, 0x81, v200
	v_sub_u32_e32 v152, 0x82, v200
	v_sub_u32_e32 v153, 0x83, v200
	v_cmp_lt_u32_e64 s[94:95], s91, v150
	v_cmp_lt_u32_e64 s[86:87], s91, v151
	v_cmp_lt_u32_e64 s[0:1], s91, v152
	v_cmp_lt_u32_e64 s[2:3], s91, v153
	v_cndmask_b32_e64 v32, v32, v230, s[94:95]
	v_cndmask_b32_e64 v33, v33, v230, s[86:87]
	v_cndmask_b32_e64 v34, v34, v230, s[0:1]
	v_cndmask_b32_e64 v35, v35, v230, s[2:3]

.Latt_noedge_4:
	s_nop 1
	v_max3_f32 v186, v36, v37, v38
	v_max3_f32 v186, v186, v39, v40
	v_max3_f32 v186, v186, v41, v42
	v_max3_f32 v186, v186, v43, v44
	v_max3_f32 v186, v186, v45, v46
	v_max3_f32 v186, v186, v47, v48
	v_max3_f32 v186, v186, v49, v50
	v_max3_f32 v186, v186, v51, v52
	v_max3_f32 v186, v186, v53, v54
	v_max3_f32 v186, v186, v55, v56
	v_max3_f32 v186, v186, v57, v58
	v_max3_f32 v186, v186, v59, v60
	v_max3_f32 v186, v186, v61, v62
	v_max3_f32 v186, v186, v63, v64
	v_max3_f32 v186, v186, v65, v66
	v_max3_f32 v186, v186, v67, v68
	v_max3_f32 v186, v186, v69, v70
	v_max_f32_e32 v186, v186, v71
	v_mov_b32_e32 v146, v186
	s_nop 1
	v_permlane16_swap_b32_e32 v186, v146
	v_max_f32_e32 v186, v186, v146
	v_mov_b32_e32 v146, v186
	s_nop 1
	v_permlane32_swap_b32_e32 v186, v146
	v_max_f32_e32 v186, v186, v146
	s_waitcnt lgkmcnt(0)
	s_add_i32 s93, s76, 64
	s_mov_b32 m0, s16
	v_add_u32_e32 v164, s93, v231
	v_med3_i32 v164, v164, 0, s40
	v_lshl_or_b32 v164, v164, 7, v222
	global_load_lds_dwordx4 v164, s[24:25]
	s_add_i32 m0, s16, 0x400
	v_add_u32_e32 v165, s93, v232
	v_med3_i32 v165, v165, 0, s40
	v_lshl_or_b32 v165, v165, 7, v222
	global_load_lds_dwordx4 v165, s[24:25]
	s_waitcnt vmcnt(8)
	v_add_u32_e32 v154, s12, v225
	v_add_u32_e32 v155, s12, v226
	v_add_u32_e32 v156, s12, v227
	v_add_u32_e32 v157, s12, v228
	ds_read_b64_tr_b16 v[202:203], v154
	ds_read_b64_tr_b16 v[204:205], v155
	ds_read_b64_tr_b16 v[206:207], v156
	ds_read_b64_tr_b16 v[208:209], v157
	v_mfma_f32_16x16x16_bf16 v[96:99], v[88:89], v[0:1], 0
	v_mfma_f32_16x16x16_bf16 v[100:103], v[90:91], v[0:1], 0
	v_mfma_f32_16x16x16_bf16 v[104:107], v[92:93], v[0:1], 0
	v_mfma_f32_16x16x16_bf16 v[108:111], v[94:95], v[0:1], 0
	v_pk_add_f32 v[36:37], v[36:37], v[186:187] op_sel_hi:[1,0] neg_lo:[0,1] neg_hi:[0,1]
	v_pk_add_f32 v[38:39], v[38:39], v[186:187] op_sel_hi:[1,0] neg_lo:[0,1] neg_hi:[0,1]
	v_exp_f32_e32 v36, v36
	v_exp_f32_e32 v37, v37
	v_exp_f32_e32 v38, v38
	v_exp_f32_e32 v39, v39
	s_nop 0
	v_pk_add_f32 v[76:77], v[36:37], v[38:39]
	v_cvt_pk_bf16_f32 v36, v36, v37
	v_cvt_pk_bf16_f32 v37, v38, v39
	s_waitcnt lgkmcnt(0)
	s_add_i32 s93, s76, 0x80
	s_mov_b32 m0, s12
	v_add_u32_e32 v164, s93, v231
	v_med3_i32 v164, v164, 0, s40
	v_lshl_or_b32 v164, v164, 7, v222
	global_load_lds_dwordx4 v164, s[24:25]
	s_add_i32 m0, s12, 0x400
	v_add_u32_e32 v165, s93, v232
	v_med3_i32 v165, v165, 0, s40
	v_lshl_or_b32 v165, v165, 7, v222
	global_load_lds_dwordx4 v165, s[24:25]
	s_waitcnt vmcnt(8)
	v_add_u32_e32 v154, s13, v225
	v_add_u32_e32 v155, s13, v226
	v_add_u32_e32 v156, s13, v227
	v_add_u32_e32 v157, s13, v228
	ds_read_b64_tr_b16 v[88:89], v154
	ds_read_b64_tr_b16 v[90:91], v155
	ds_read_b64_tr_b16 v[92:93], v156
	ds_read_b64_tr_b16 v[94:95], v157
	v_mfma_f32_16x16x16_bf16 v[96:99], v[202:203], v[4:5], v[96:99]
	v_mfma_f32_16x16x16_bf16 v[112:115], v[202:203], v[36:37], 0
	v_mfma_f32_16x16x16_bf16 v[100:103], v[204:205], v[4:5], v[100:103]
	v_mfma_f32_16x16x16_bf16 v[116:119], v[204:205], v[36:37], 0
	v_mfma_f32_16x16x16_bf16 v[104:107], v[206:207], v[4:5], v[104:107]
	v_mfma_f32_16x16x16_bf16 v[120:123], v[206:207], v[36:37], 0
	v_mfma_f32_16x16x16_bf16 v[108:111], v[208:209], v[4:5], v[108:111]
	v_mfma_f32_16x16x16_bf16 v[124:127], v[208:209], v[36:37], 0
	v_pk_add_f32 v[40:41], v[40:41], v[186:187] op_sel_hi:[1,0] neg_lo:[0,1] neg_hi:[0,1]
	v_pk_add_f32 v[42:43], v[42:43], v[186:187] op_sel_hi:[1,0] neg_lo:[0,1] neg_hi:[0,1]
	v_exp_f32_e32 v40, v40
	v_exp_f32_e32 v41, v41
	v_exp_f32_e32 v42, v42
	v_exp_f32_e32 v43, v43
	s_nop 0
	v_pk_add_f32 v[78:79], v[40:41], v[42:43]
	v_cvt_pk_bf16_f32 v40, v40, v41
	v_cvt_pk_bf16_f32 v41, v42, v43
	s_waitcnt lgkmcnt(0)
	s_add_i32 s93, s76, 0xc0
	s_mov_b32 m0, s13
	v_add_u32_e32 v164, s93, v231
	v_med3_i32 v164, v164, 0, s40
	v_lshl_or_b32 v164, v164, 7, v222
	global_load_lds_dwordx4 v164, s[24:25]
	s_add_i32 m0, s13, 0x400
	v_add_u32_e32 v165, s93, v232
	v_med3_i32 v165, v165, 0, s40
	v_lshl_or_b32 v165, v165, 7, v222
	global_load_lds_dwordx4 v165, s[24:25]
	s_waitcnt vmcnt(8)
	v_add_u32_e32 v154, s14, v225
	v_add_u32_e32 v155, s14, v226
	v_add_u32_e32 v156, s14, v227
	v_add_u32_e32 v157, s14, v228
	ds_read_b64_tr_b16 v[202:203], v154
	ds_read_b64_tr_b16 v[204:205], v155
	ds_read_b64_tr_b16 v[206:207], v156
	ds_read_b64_tr_b16 v[208:209], v157
	v_mfma_f32_16x16x16_bf16 v[96:99], v[88:89], v[8:9], v[96:99]
	v_mfma_f32_16x16x16_bf16 v[112:115], v[88:89], v[40:41], v[112:115]
	v_mfma_f32_16x16x16_bf16 v[100:103], v[90:91], v[8:9], v[100:103]
	v_mfma_f32_16x16x16_bf16 v[116:119], v[90:91], v[40:41], v[116:119]
	v_mfma_f32_16x16x16_bf16 v[104:107], v[92:93], v[8:9], v[104:107]
	v_mfma_f32_16x16x16_bf16 v[120:123], v[92:93], v[40:41], v[120:123]
	v_mfma_f32_16x16x16_bf16 v[108:111], v[94:95], v[8:9], v[108:111]
	v_mfma_f32_16x16x16_bf16 v[124:127], v[94:95], v[40:41], v[124:127]
	v_pk_add_f32 v[44:45], v[44:45], v[186:187] op_sel_hi:[1,0] neg_lo:[0,1] neg_hi:[0,1]
	v_pk_add_f32 v[46:47], v[46:47], v[186:187] op_sel_hi:[1,0] neg_lo:[0,1] neg_hi:[0,1]
	v_exp_f32_e32 v44, v44
	v_exp_f32_e32 v45, v45
	v_exp_f32_e32 v46, v46
	v_exp_f32_e32 v47, v47
	s_nop 0
	v_pk_add_f32 v[76:77], v[76:77], v[44:45]
	v_pk_add_f32 v[78:79], v[78:79], v[46:47]
	v_cvt_pk_bf16_f32 v44, v44, v45
	v_cvt_pk_bf16_f32 v45, v46, v47
	s_waitcnt lgkmcnt(0)
	s_add_i32 s93, s76, 0x100
	s_mov_b32 m0, s14
	v_add_u32_e32 v164, s93, v231
	v_med3_i32 v164, v164, 0, s40
	v_lshl_or_b32 v164, v164, 7, v222
	global_load_lds_dwordx4 v164, s[24:25]
	s_add_i32 m0, s14, 0x400
	v_add_u32_e32 v165, s93, v232
	v_med3_i32 v165, v165, 0, s40
	v_lshl_or_b32 v165, v165, 7, v222
	global_load_lds_dwordx4 v165, s[24:25]
	s_waitcnt vmcnt(8)
	v_add_u32_e32 v154, s15, v225
	v_add_u32_e32 v155, s15, v226
	v_add_u32_e32 v156, s15, v227
	v_add_u32_e32 v157, s15, v228
	ds_read_b64_tr_b16 v[88:89], v154
	ds_read_b64_tr_b16 v[90:91], v155
	ds_read_b64_tr_b16 v[92:93], v156
	ds_read_b64_tr_b16 v[94:95], v157
	v_mfma_f32_16x16x16_bf16 v[96:99], v[202:203], v[12:13], v[96:99]
	v_mfma_f32_16x16x16_bf16 v[112:115], v[202:203], v[44:45], v[112:115]
	v_mfma_f32_16x16x16_bf16 v[100:103], v[204:205], v[12:13], v[100:103]
	v_mfma_f32_16x16x16_bf16 v[116:119], v[204:205], v[44:45], v[116:119]
	v_mfma_f32_16x16x16_bf16 v[104:107], v[206:207], v[12:13], v[104:107]
	v_mfma_f32_16x16x16_bf16 v[120:123], v[206:207], v[44:45], v[120:123]
	v_mfma_f32_16x16x16_bf16 v[108:111], v[208:209], v[12:13], v[108:111]
	v_mfma_f32_16x16x16_bf16 v[124:127], v[208:209], v[44:45], v[124:127]
	v_pk_add_f32 v[48:49], v[48:49], v[186:187] op_sel_hi:[1,0] neg_lo:[0,1] neg_hi:[0,1]
	v_pk_add_f32 v[50:51], v[50:51], v[186:187] op_sel_hi:[1,0] neg_lo:[0,1] neg_hi:[0,1]
	v_exp_f32_e32 v48, v48
	v_exp_f32_e32 v49, v49
	v_exp_f32_e32 v50, v50
	v_exp_f32_e32 v51, v51
	s_nop 0
	v_pk_add_f32 v[76:77], v[76:77], v[48:49]
	v_pk_add_f32 v[78:79], v[78:79], v[50:51]
	v_cvt_pk_bf16_f32 v48, v48, v49
	v_cvt_pk_bf16_f32 v49, v50, v51
	s_waitcnt lgkmcnt(0)
	s_add_i32 s93, s76, 0x140
	s_mov_b32 m0, s15
	v_add_u32_e32 v164, s93, v231
	v_med3_i32 v164, v164, 0, s40
	v_lshl_or_b32 v164, v164, 7, v222
	global_load_lds_dwordx4 v164, s[24:25]
	s_add_i32 m0, s15, 0x400
	v_add_u32_e32 v165, s93, v232
	v_med3_i32 v165, v165, 0, s40
	v_lshl_or_b32 v165, v165, 7, v222
	global_load_lds_dwordx4 v165, s[24:25]
	s_waitcnt vmcnt(8)
	v_add_u32_e32 v154, s16, v225
	v_add_u32_e32 v155, s16, v226
	v_add_u32_e32 v156, s16, v227
	v_add_u32_e32 v157, s16, v228
	ds_read_b64_tr_b16 v[202:203], v154
	ds_read_b64_tr_b16 v[204:205], v155
	ds_read_b64_tr_b16 v[206:207], v156
	ds_read_b64_tr_b16 v[208:209], v157
	v_mfma_f32_16x16x16_bf16 v[96:99], v[88:89], v[16:17], v[96:99]
	v_mfma_f32_16x16x16_bf16 v[112:115], v[88:89], v[48:49], v[112:115]
	v_mfma_f32_16x16x16_bf16 v[100:103], v[90:91], v[16:17], v[100:103]
	v_mfma_f32_16x16x16_bf16 v[116:119], v[90:91], v[48:49], v[116:119]
	v_mfma_f32_16x16x16_bf16 v[104:107], v[92:93], v[16:17], v[104:107]
	v_mfma_f32_16x16x16_bf16 v[120:123], v[92:93], v[48:49], v[120:123]
	v_mfma_f32_16x16x16_bf16 v[108:111], v[94:95], v[16:17], v[108:111]
	v_mfma_f32_16x16x16_bf16 v[124:127], v[94:95], v[48:49], v[124:127]
	v_pk_add_f32 v[52:53], v[52:53], v[186:187] op_sel_hi:[1,0] neg_lo:[0,1] neg_hi:[0,1]
	v_pk_add_f32 v[54:55], v[54:55], v[186:187] op_sel_hi:[1,0] neg_lo:[0,1] neg_hi:[0,1]
	v_exp_f32_e32 v52, v52
	v_exp_f32_e32 v53, v53
	v_exp_f32_e32 v54, v54
	v_exp_f32_e32 v55, v55
	s_nop 0
	v_pk_add_f32 v[76:77], v[76:77], v[52:53]
	v_pk_add_f32 v[78:79], v[78:79], v[54:55]
	v_cvt_pk_bf16_f32 v52, v52, v53
	v_cvt_pk_bf16_f32 v53, v54, v55
	s_waitcnt lgkmcnt(0)
	s_add_i32 s93, s79, 0
	s_mov_b32 m0, s16
	v_add_u32_e32 v164, s93, v162
	v_lshl_or_b32 v164, v164, 7, v220
	global_load_lds_dwordx4 v164, s[18:19]
	s_add_i32 m0, s16, 0x400
	v_add_u32_e32 v165, s93, v163
	v_lshl_or_b32 v165, v165, 7, v221
	global_load_lds_dwordx4 v165, s[18:19]
	s_waitcnt vmcnt(8)
	v_add_u32_e32 v154, s12, v225
	v_add_u32_e32 v155, s12, v226
	v_add_u32_e32 v156, s12, v227
	v_add_u32_e32 v157, s12, v228
	ds_read_b64_tr_b16 v[88:89], v154
	ds_read_b64_tr_b16 v[90:91], v155
	ds_read_b64_tr_b16 v[92:93], v156
	ds_read_b64_tr_b16 v[94:95], v157
	v_mfma_f32_16x16x16_bf16 v[96:99], v[202:203], v[20:21], v[96:99]
	v_mfma_f32_16x16x16_bf16 v[112:115], v[202:203], v[52:53], v[112:115]
	v_mfma_f32_16x16x16_bf16 v[100:103], v[204:205], v[20:21], v[100:103]
	v_mfma_f32_16x16x16_bf16 v[116:119], v[204:205], v[52:53], v[116:119]
	v_mfma_f32_16x16x16_bf16 v[104:107], v[206:207], v[20:21], v[104:107]
	v_mfma_f32_16x16x16_bf16 v[120:123], v[206:207], v[52:53], v[120:123]
	v_mfma_f32_16x16x16_bf16 v[108:111], v[208:209], v[20:21], v[108:111]
	v_mfma_f32_16x16x16_bf16 v[124:127], v[208:209], v[52:53], v[124:127]
	v_pk_add_f32 v[56:57], v[56:57], v[186:187] op_sel_hi:[1,0] neg_lo:[0,1] neg_hi:[0,1]
	v_pk_add_f32 v[58:59], v[58:59], v[186:187] op_sel_hi:[1,0] neg_lo:[0,1] neg_hi:[0,1]
	v_exp_f32_e32 v56, v56
	v_exp_f32_e32 v57, v57
	v_exp_f32_e32 v58, v58
	v_exp_f32_e32 v59, v59
	s_nop 0
	v_pk_add_f32 v[76:77], v[76:77], v[56:57]
	v_pk_add_f32 v[78:79], v[78:79], v[58:59]
	v_cvt_pk_bf16_f32 v56, v56, v57
	v_cvt_pk_bf16_f32 v57, v58, v59
	s_waitcnt lgkmcnt(0)
	s_add_i32 s93, s79, 0xfffffc00
	s_mov_b32 m0, s12
	v_add_u32_e32 v164, s93, v162
	v_med3_i32 v164, v164, 0, s40
	v_lshl_or_b32 v164, v164, 7, v220
	global_load_lds_dwordx4 v164, s[20:21]
	s_add_i32 m0, s12, 0x400
	v_add_u32_e32 v165, s93, v163
	v_med3_i32 v165, v165, 0, s40
	v_lshl_or_b32 v165, v165, 7, v221
	global_load_lds_dwordx4 v165, s[20:21]
	s_waitcnt vmcnt(8)
	v_add_u32_e32 v154, s13, v225
	v_add_u32_e32 v155, s13, v226
	v_add_u32_e32 v156, s13, v227
	v_add_u32_e32 v157, s13, v228
	ds_read_b64_tr_b16 v[202:203], v154
	ds_read_b64_tr_b16 v[204:205], v155
	ds_read_b64_tr_b16 v[206:207], v156
	ds_read_b64_tr_b16 v[208:209], v157
	v_mfma_f32_16x16x16_bf16 v[96:99], v[88:89], v[24:25], v[96:99]
	v_mfma_f32_16x16x16_bf16 v[112:115], v[88:89], v[56:57], v[112:115]
	v_mfma_f32_16x16x16_bf16 v[100:103], v[90:91], v[24:25], v[100:103]
	v_mfma_f32_16x16x16_bf16 v[116:119], v[90:91], v[56:57], v[116:119]
	v_mfma_f32_16x16x16_bf16 v[104:107], v[92:93], v[24:25], v[104:107]
	v_mfma_f32_16x16x16_bf16 v[120:123], v[92:93], v[56:57], v[120:123]
	v_mfma_f32_16x16x16_bf16 v[108:111], v[94:95], v[24:25], v[108:111]
	v_mfma_f32_16x16x16_bf16 v[124:127], v[94:95], v[56:57], v[124:127]
	v_pk_add_f32 v[60:61], v[60:61], v[186:187] op_sel_hi:[1,0] neg_lo:[0,1] neg_hi:[0,1]
	v_pk_add_f32 v[62:63], v[62:63], v[186:187] op_sel_hi:[1,0] neg_lo:[0,1] neg_hi:[0,1]
	v_exp_f32_e32 v60, v60
	v_exp_f32_e32 v61, v61
	v_exp_f32_e32 v62, v62
	v_exp_f32_e32 v63, v63
	s_nop 0
	v_pk_add_f32 v[76:77], v[76:77], v[60:61]
	v_pk_add_f32 v[78:79], v[78:79], v[62:63]
	v_cvt_pk_bf16_f32 v60, v60, v61
	v_cvt_pk_bf16_f32 v61, v62, v63
	s_waitcnt lgkmcnt(0)
	s_add_i32 s93, s79, 0xfffffd00
	s_mov_b32 m0, s13
	v_add_u32_e32 v164, s93, v162
	v_med3_i32 v164, v164, 0, s40
	v_lshl_or_b32 v164, v164, 7, v220
	global_load_lds_dwordx4 v164, s[20:21]
	s_add_i32 m0, s13, 0x400
	v_add_u32_e32 v165, s93, v163
	v_med3_i32 v165, v165, 0, s40
	v_lshl_or_b32 v165, v165, 7, v221
	global_load_lds_dwordx4 v165, s[20:21]
	s_waitcnt vmcnt(8)
	v_add_u32_e32 v154, s14, v225
	v_add_u32_e32 v155, s14, v226
	v_add_u32_e32 v156, s14, v227
	v_add_u32_e32 v157, s14, v228
	ds_read_b64_tr_b16 v[88:89], v154
	ds_read_b64_tr_b16 v[90:91], v155
	ds_read_b64_tr_b16 v[92:93], v156
	ds_read_b64_tr_b16 v[94:95], v157
	v_mfma_f32_16x16x16_bf16 v[96:99], v[202:203], v[28:29], v[96:99]
	v_mfma_f32_16x16x16_bf16 v[112:115], v[202:203], v[60:61], v[112:115]
	v_mfma_f32_16x16x16_bf16 v[100:103], v[204:205], v[28:29], v[100:103]
	v_mfma_f32_16x16x16_bf16 v[116:119], v[204:205], v[60:61], v[116:119]
	v_mfma_f32_16x16x16_bf16 v[104:107], v[206:207], v[28:29], v[104:107]
	v_mfma_f32_16x16x16_bf16 v[120:123], v[206:207], v[60:61], v[120:123]
	v_mfma_f32_16x16x16_bf16 v[108:111], v[208:209], v[28:29], v[108:111]
	v_mfma_f32_16x16x16_bf16 v[124:127], v[208:209], v[60:61], v[124:127]
	v_pk_add_f32 v[64:65], v[64:65], v[186:187] op_sel_hi:[1,0] neg_lo:[0,1] neg_hi:[0,1]
	v_pk_add_f32 v[66:67], v[66:67], v[186:187] op_sel_hi:[1,0] neg_lo:[0,1] neg_hi:[0,1]
	v_exp_f32_e32 v64, v64
	v_exp_f32_e32 v65, v65
	v_exp_f32_e32 v66, v66
	v_exp_f32_e32 v67, v67
	s_nop 0
	v_pk_add_f32 v[76:77], v[76:77], v[64:65]
	v_pk_add_f32 v[78:79], v[78:79], v[66:67]
	v_cvt_pk_bf16_f32 v64, v64, v65
	v_cvt_pk_bf16_f32 v65, v66, v67
	s_waitcnt lgkmcnt(0)
	s_add_i32 s93, s79, 0xfffffe00
	s_mov_b32 m0, s14
	v_add_u32_e32 v164, s93, v162
	v_med3_i32 v164, v164, 0, s40
	v_lshl_or_b32 v164, v164, 7, v220
	global_load_lds_dwordx4 v164, s[20:21]
	s_add_i32 m0, s14, 0x400
	v_add_u32_e32 v165, s93, v163
	v_med3_i32 v165, v165, 0, s40
	v_lshl_or_b32 v165, v165, 7, v221
	global_load_lds_dwordx4 v165, s[20:21]
	s_waitcnt vmcnt(8)
	v_add_u32_e32 v154, s15, v225
	v_add_u32_e32 v155, s15, v226
	v_add_u32_e32 v156, s15, v227
	v_add_u32_e32 v157, s15, v228
	ds_read_b64_tr_b16 v[202:203], v154
	ds_read_b64_tr_b16 v[204:205], v155
	ds_read_b64_tr_b16 v[206:207], v156
	ds_read_b64_tr_b16 v[208:209], v157
	v_mfma_f32_16x16x16_bf16 v[96:99], v[88:89], v[32:33], v[96:99]
	v_mfma_f32_16x16x16_bf16 v[112:115], v[88:89], v[64:65], v[112:115]
	v_mfma_f32_16x16x16_bf16 v[100:103], v[90:91], v[32:33], v[100:103]
	v_mfma_f32_16x16x16_bf16 v[116:119], v[90:91], v[64:65], v[116:119]
	v_mfma_f32_16x16x16_bf16 v[104:107], v[92:93], v[32:33], v[104:107]
	v_mfma_f32_16x16x16_bf16 v[120:123], v[92:93], v[64:65], v[120:123]
	v_mfma_f32_16x16x16_bf16 v[108:111], v[94:95], v[32:33], v[108:111]
	v_mfma_f32_16x16x16_bf16 v[124:127], v[94:95], v[64:65], v[124:127]
	v_pk_add_f32 v[68:69], v[68:69], v[186:187] op_sel_hi:[1,0] neg_lo:[0,1] neg_hi:[0,1]
	v_pk_add_f32 v[70:71], v[70:71], v[186:187] op_sel_hi:[1,0] neg_lo:[0,1] neg_hi:[0,1]
	v_exp_f32_e32 v68, v68
	v_exp_f32_e32 v69, v69
	v_exp_f32_e32 v70, v70
	v_exp_f32_e32 v71, v71
	s_nop 0
	v_pk_add_f32 v[76:77], v[76:77], v[68:69]
	v_pk_add_f32 v[78:79], v[78:79], v[70:71]
	v_cvt_pk_bf16_f32 v68, v68, v69
	v_cvt_pk_bf16_f32 v69, v70, v71
	s_waitcnt lgkmcnt(0)
	s_add_i32 s93, s79, 0xffffff00
	s_mov_b32 m0, s15
	v_add_u32_e32 v164, s93, v162
	v_med3_i32 v164, v164, 0, s40
	v_lshl_or_b32 v164, v164, 7, v220
	global_load_lds_dwordx4 v164, s[20:21]
	s_add_i32 m0, s15, 0x400
	v_add_u32_e32 v165, s93, v163
	v_med3_i32 v165, v165, 0, s40
	v_lshl_or_b32 v165, v165, 7, v221
	global_load_lds_dwordx4 v165, s[20:21]
	v_mfma_f32_16x16x16_bf16 v[112:115], v[202:203], v[68:69], v[112:115]
	v_mfma_f32_16x16x16_bf16 v[116:119], v[204:205], v[68:69], v[116:119]
	v_mfma_f32_16x16x16_bf16 v[120:123], v[206:207], v[68:69], v[120:123]
	v_mfma_f32_16x16x16_bf16 v[124:127], v[208:209], v[68:69], v[124:127]
	s_nop 0
	v_pk_add_f32 v[76:77], v[76:77], v[78:79]
	s_nop 0
	v_add_f32_e32 v187, v76, v77
	v_mov_b32_e32 v146, v187
	s_nop 1
	v_permlane16_swap_b32_e32 v187, v146
	v_add_f32_e32 v187, v187, v146
	v_mov_b32_e32 v146, v187
	s_nop 1
	v_permlane32_swap_b32_e32 v187, v146
	v_add_f32_e32 v187, v187, v146
	s_waitcnt lgkmcnt(0)
	v_max_f32_e32 v146, v144, v184
	v_sub_f32_e32 v148, v144, v146
	v_sub_f32_e32 v150, v184, v146
	v_exp_f32_e32 v148, v148
	v_exp_f32_e32 v150, v150
	v_mov_b32_e32 v184, v146
	v_mul_f32_e32 v185, v185, v150
	v_fmac_f32_e32 v185, v145, v148
	v_pk_mul_f32 v[96:97], v[150:151], v[96:97] op_sel_hi:[0,1]
	v_pk_mul_f32 v[98:99], v[150:151], v[98:99] op_sel_hi:[0,1]
	v_pk_mul_f32 v[100:101], v[150:151], v[100:101] op_sel_hi:[0,1]
	v_pk_mul_f32 v[102:103], v[150:151], v[102:103] op_sel_hi:[0,1]
	v_pk_mul_f32 v[104:105], v[150:151], v[104:105] op_sel_hi:[0,1]
	v_pk_mul_f32 v[106:107], v[150:151], v[106:107] op_sel_hi:[0,1]
	v_pk_mul_f32 v[108:109], v[150:151], v[108:109] op_sel_hi:[0,1]
	v_pk_mul_f32 v[110:111], v[150:151], v[110:111] op_sel_hi:[0,1]
	v_pk_fma_f32 v[96:97], v[148:149], v[128:129], v[96:97] op_sel_hi:[0,1,1]
	v_pk_fma_f32 v[98:99], v[148:149], v[130:131], v[98:99] op_sel_hi:[0,1,1]
	v_pk_fma_f32 v[100:101], v[148:149], v[132:133], v[100:101] op_sel_hi:[0,1,1]
	v_pk_fma_f32 v[102:103], v[148:149], v[134:135], v[102:103] op_sel_hi:[0,1,1]
	v_pk_fma_f32 v[104:105], v[148:149], v[136:137], v[104:105] op_sel_hi:[0,1,1]
	v_pk_fma_f32 v[106:107], v[148:149], v[138:139], v[106:107] op_sel_hi:[0,1,1]
	v_pk_fma_f32 v[108:109], v[148:149], v[140:141], v[108:109] op_sel_hi:[0,1,1]
	v_pk_fma_f32 v[110:111], v[148:149], v[142:143], v[110:111] op_sel_hi:[0,1,1]
	s_and_saveexec_b64 s[80:81], s[74:75]
	ds_write_b64 v194, v[184:185]
	s_mov_b64 exec, s[80:81]
	ds_write_b128 v190, v[96:99]
	ds_write_b128 v191, v[100:103]
	ds_write_b128 v192, v[104:107]
	ds_write_b128 v193, v[108:111]
	s_waitcnt lgkmcnt(0)
	v_max_f32_e32 v146, v182, v186
	v_sub_f32_e32 v148, v182, v146
	v_sub_f32_e32 v150, v186, v146
	v_exp_f32_e32 v148, v148
	v_exp_f32_e32 v150, v150
	v_mov_b32_e32 v186, v146
	v_mul_f32_e32 v187, v187, v150
	v_fmac_f32_e32 v187, v183, v148
	v_pk_mul_f32 v[112:113], v[150:151], v[112:113] op_sel_hi:[0,1]
	v_pk_mul_f32 v[114:115], v[150:151], v[114:115] op_sel_hi:[0,1]
	v_pk_mul_f32 v[116:117], v[150:151], v[116:117] op_sel_hi:[0,1]
	v_pk_mul_f32 v[118:119], v[150:151], v[118:119] op_sel_hi:[0,1]
	v_pk_mul_f32 v[120:121], v[150:151], v[120:121] op_sel_hi:[0,1]
	v_pk_mul_f32 v[122:123], v[150:151], v[122:123] op_sel_hi:[0,1]
	v_pk_mul_f32 v[124:125], v[150:151], v[124:125] op_sel_hi:[0,1]
	v_pk_mul_f32 v[126:127], v[150:151], v[126:127] op_sel_hi:[0,1]
	v_pk_fma_f32 v[112:113], v[148:149], v[166:167], v[112:113] op_sel_hi:[0,1,1]
	v_pk_fma_f32 v[114:115], v[148:149], v[168:169], v[114:115] op_sel_hi:[0,1,1]
	v_pk_fma_f32 v[116:117], v[148:149], v[170:171], v[116:117] op_sel_hi:[0,1,1]
	v_pk_fma_f32 v[118:119], v[148:149], v[172:173], v[118:119] op_sel_hi:[0,1,1]
	v_pk_fma_f32 v[120:121], v[148:149], v[174:175], v[120:121] op_sel_hi:[0,1,1]
	v_pk_fma_f32 v[122:123], v[148:149], v[176:177], v[122:123] op_sel_hi:[0,1,1]
	v_pk_fma_f32 v[124:125], v[148:149], v[178:179], v[124:125] op_sel_hi:[0,1,1]
	v_pk_fma_f32 v[126:127], v[148:149], v[180:181], v[126:127] op_sel_hi:[0,1,1]
	s_and_saveexec_b64 s[80:81], s[74:75]
	ds_write_b64 v199, v[186:187]
	s_mov_b64 exec, s[80:81]
	ds_write_b128 v195, v[112:115]
	ds_write_b128 v196, v[116:119]
	ds_write_b128 v197, v[120:123]
	ds_write_b128 v198, v[124:127]
	s_waitcnt lgkmcnt(0)
	s_barrier
	s_add_i32 s76, s38, s84
	s_add_i32 s79, s39, s82
	v_lshlrev_b32_e32 v231, 4, v218
	v_add_u32_e32 v232, 8, v218
	v_lshlrev_b32_e32 v232, 4, v232
	v_lshlrev_b32_e32 v162, 0, v218
	v_add_u32_e32 v163, 8, v218
	v_lshlrev_b32_e32 v163, 0, v163
	s_add_i32 s8, s38, s85
	s_waitcnt vmcnt(8)
	v_add_u32_e32 v154, s16, v223
	v_add_u32_e32 v155, s16, v224
	ds_read_b128 v[72:75], v154
	ds_read_b128 v[76:79], v155
	s_waitcnt lgkmcnt(0)
	s_add_i32 s93, s76, 0
	s_mov_b32 m0, s16
	v_add_u32_e32 v164, s93, v231
	v_med3_i32 v164, v164, 0, s40
	v_lshl_or_b32 v164, v164, 7, v220
	global_load_lds_dwordx4 v164, s[20:21]
	s_add_i32 m0, s16, 0x400
	v_add_u32_e32 v165, s93, v232
	v_med3_i32 v165, v165, 0, s40
	v_lshl_or_b32 v165, v165, 7, v221
	global_load_lds_dwordx4 v165, s[20:21]
	s_waitcnt vmcnt(8)
	v_add_u32_e32 v154, s12, v223
	v_add_u32_e32 v155, s12, v224
	ds_read_b128 v[202:205], v154
	ds_read_b128 v[206:209], v155
	s_waitcnt lgkmcnt(0)
	s_add_i32 s93, s76, 0x100
	s_mov_b32 m0, s12
	v_add_u32_e32 v164, s93, v231
	v_med3_i32 v164, v164, 0, s40
	v_lshl_or_b32 v164, v164, 7, v220
	global_load_lds_dwordx4 v164, s[20:21]
	s_add_i32 m0, s12, 0x400
	v_add_u32_e32 v165, s93, v232
	v_med3_i32 v165, v165, 0, s40
	v_lshl_or_b32 v165, v165, 7, v221
	global_load_lds_dwordx4 v165, s[20:21]
	s_waitcnt vmcnt(8)
	v_add_u32_e32 v154, s13, v223
	v_add_u32_e32 v155, s13, v224
	ds_read_b128 v[88:91], v154
	ds_read_b128 v[92:95], v155
	v_mfma_f32_16x16x32_bf16 v[0:3], v[202:205], v[72:75], 0
	v_mfma_f32_16x16x32_bf16 v[0:3], v[206:209], v[76:79], v[0:3]
	s_waitcnt lgkmcnt(0)
	s_add_i32 s93, s76, 0x200
	s_mov_b32 m0, s13
	v_add_u32_e32 v164, s93, v231
	v_med3_i32 v164, v164, 0, s40
	v_lshl_or_b32 v164, v164, 7, v220
	global_load_lds_dwordx4 v164, s[20:21]
	s_add_i32 m0, s13, 0x400
	v_add_u32_e32 v165, s93, v232
	v_med3_i32 v165, v165, 0, s40
	v_lshl_or_b32 v165, v165, 7, v221
	global_load_lds_dwordx4 v165, s[20:21]
	s_waitcnt vmcnt(8)
	v_add_u32_e32 v154, s14, v223
	v_add_u32_e32 v155, s14, v224
	ds_read_b128 v[202:205], v154
	ds_read_b128 v[206:209], v155
	v_mfma_f32_16x16x32_bf16 v[4:7], v[88:91], v[72:75], 0
	v_mfma_f32_16x16x32_bf16 v[4:7], v[92:95], v[76:79], v[4:7]
	s_waitcnt lgkmcnt(0)
	s_add_i32 s93, s76, 0x300
	s_mov_b32 m0, s14
	v_add_u32_e32 v164, s93, v231
	v_med3_i32 v164, v164, 0, s40
	v_lshl_or_b32 v164, v164, 7, v220
	global_load_lds_dwordx4 v164, s[20:21]
	s_add_i32 m0, s14, 0x400
	v_add_u32_e32 v165, s93, v232
	v_med3_i32 v165, v165, 0, s40
	v_lshl_or_b32 v165, v165, 7, v221
	global_load_lds_dwordx4 v165, s[20:21]
	s_waitcnt vmcnt(8)
	v_add_u32_e32 v154, s15, v223
	v_add_u32_e32 v155, s15, v224
	ds_read_b128 v[88:91], v154
	ds_read_b128 v[92:95], v155
	v_mfma_f32_16x16x32_bf16 v[8:11], v[202:205], v[72:75], 0
	v_mfma_f32_16x16x32_bf16 v[8:11], v[206:209], v[76:79], v[8:11]
	s_waitcnt lgkmcnt(0)
	s_add_i32 s93, s76, 0x400
	s_mov_b32 m0, s15
	v_add_u32_e32 v164, s93, v231
	v_med3_i32 v164, v164, 0, s40
	v_lshl_or_b32 v164, v164, 7, v220
	global_load_lds_dwordx4 v164, s[20:21]
	s_add_i32 m0, s15, 0x400
	v_add_u32_e32 v165, s93, v232
	v_med3_i32 v165, v165, 0, s40
	v_lshl_or_b32 v165, v165, 7, v221
	global_load_lds_dwordx4 v165, s[20:21]
	s_waitcnt vmcnt(8)
	v_add_u32_e32 v154, s16, v223
	v_add_u32_e32 v155, s16, v224
	ds_read_b128 v[202:205], v154
	ds_read_b128 v[206:209], v155
	v_mfma_f32_16x16x32_bf16 v[12:15], v[88:91], v[72:75], 0
	v_mfma_f32_16x16x32_bf16 v[12:15], v[92:95], v[76:79], v[12:15]
	s_waitcnt lgkmcnt(0)
	s_add_i32 s93, s8, 0
	s_mov_b32 m0, s16
	v_add_u32_e32 v164, s93, v231
	v_lshl_or_b32 v164, v164, 7, v220
	global_load_lds_dwordx4 v164, s[18:19]
	s_add_i32 m0, s16, 0x400
	v_add_u32_e32 v165, s93, v232
	v_lshl_or_b32 v165, v165, 7, v221
	global_load_lds_dwordx4 v165, s[18:19]
	s_waitcnt vmcnt(8)
	v_add_u32_e32 v154, s12, v223
	v_add_u32_e32 v155, s12, v224
	ds_read_b128 v[88:91], v154
	ds_read_b128 v[92:95], v155
	v_mfma_f32_16x16x32_bf16 v[16:19], v[202:205], v[72:75], 0
	v_mfma_f32_16x16x32_bf16 v[16:19], v[206:209], v[76:79], v[16:19]
	s_waitcnt lgkmcnt(0)
	s_add_i32 s93, s8, 0xfffffc00
	s_mov_b32 m0, s12
	v_add_u32_e32 v164, s93, v231
	v_med3_i32 v164, v164, 0, s40
	v_lshl_or_b32 v164, v164, 7, v220
	global_load_lds_dwordx4 v164, s[20:21]
	s_add_i32 m0, s12, 0x400
	v_add_u32_e32 v165, s93, v232
	v_med3_i32 v165, v165, 0, s40
	v_lshl_or_b32 v165, v165, 7, v221
	global_load_lds_dwordx4 v165, s[20:21]
	s_waitcnt vmcnt(8)
	v_add_u32_e32 v154, s13, v223
	v_add_u32_e32 v155, s13, v224
	ds_read_b128 v[202:205], v154
	ds_read_b128 v[206:209], v155
	v_mfma_f32_16x16x32_bf16 v[20:23], v[88:91], v[72:75], 0
	v_mfma_f32_16x16x32_bf16 v[20:23], v[92:95], v[76:79], v[20:23]
	s_waitcnt lgkmcnt(0)
	s_add_i32 s93, s8, 0xfffffd00
	s_mov_b32 m0, s13
	v_add_u32_e32 v164, s93, v231
	v_med3_i32 v164, v164, 0, s40
	v_lshl_or_b32 v164, v164, 7, v220
	global_load_lds_dwordx4 v164, s[20:21]
	s_add_i32 m0, s13, 0x400
	v_add_u32_e32 v165, s93, v232
	v_med3_i32 v165, v165, 0, s40
	v_lshl_or_b32 v165, v165, 7, v221
	global_load_lds_dwordx4 v165, s[20:21]
	s_waitcnt vmcnt(8)
	v_add_u32_e32 v154, s14, v223
	v_add_u32_e32 v155, s14, v224
	ds_read_b128 v[88:91], v154
	ds_read_b128 v[92:95], v155
	v_mfma_f32_16x16x32_bf16 v[24:27], v[202:205], v[72:75], 0
	v_mfma_f32_16x16x32_bf16 v[24:27], v[206:209], v[76:79], v[24:27]
	s_waitcnt lgkmcnt(0)
	s_add_i32 s93, s8, 0xfffffe00
	s_mov_b32 m0, s14
	v_add_u32_e32 v164, s93, v231
	v_med3_i32 v164, v164, 0, s40
	v_lshl_or_b32 v164, v164, 7, v220
	global_load_lds_dwordx4 v164, s[20:21]
	s_add_i32 m0, s14, 0x400
	v_add_u32_e32 v165, s93, v232
	v_med3_i32 v165, v165, 0, s40
	v_lshl_or_b32 v165, v165, 7, v221
	global_load_lds_dwordx4 v165, s[20:21]
	s_waitcnt vmcnt(8)
	v_add_u32_e32 v154, s15, v223
	v_add_u32_e32 v155, s15, v224
	ds_read_b128 v[202:205], v154
	ds_read_b128 v[206:209], v155
	v_mfma_f32_16x16x32_bf16 v[28:31], v[88:91], v[72:75], 0
	v_mfma_f32_16x16x32_bf16 v[28:31], v[92:95], v[76:79], v[28:31]
	s_waitcnt lgkmcnt(0)
	s_add_i32 s93, s8, 0xffffff00
	s_mov_b32 m0, s15
	v_add_u32_e32 v164, s93, v231
	v_med3_i32 v164, v164, 0, s40
	v_lshl_or_b32 v164, v164, 7, v220
	global_load_lds_dwordx4 v164, s[20:21]
	s_add_i32 m0, s15, 0x400
	v_add_u32_e32 v165, s93, v232
	v_med3_i32 v165, v165, 0, s40
	v_lshl_or_b32 v165, v165, 7, v221
	global_load_lds_dwordx4 v165, s[20:21]
	s_waitcnt vmcnt(8)
	v_add_u32_e32 v154, s16, v223
	v_add_u32_e32 v155, s16, v224
	ds_read_b128 v[80:83], v154
	ds_read_b128 v[84:87], v155
	v_mfma_f32_16x16x32_bf16 v[32:35], v[202:205], v[72:75], 0
	v_mfma_f32_16x16x32_bf16 v[32:35], v[206:209], v[76:79], v[32:35]
	s_waitcnt lgkmcnt(0)
	s_add_i32 s93, s8, 0
	s_mov_b32 m0, s16
	v_add_u32_e32 v164, s93, v231
	v_med3_i32 v164, v164, 0, s40
	v_lshl_or_b32 v164, v164, 7, v220
	global_load_lds_dwordx4 v164, s[20:21]
	s_add_i32 m0, s16, 0x400
	v_add_u32_e32 v165, s93, v232
	v_med3_i32 v165, v165, 0, s40
	v_lshl_or_b32 v165, v165, 7, v221
	global_load_lds_dwordx4 v165, s[20:21]
	s_waitcnt vmcnt(8)
	v_add_u32_e32 v154, s12, v223
	v_add_u32_e32 v155, s12, v224
	ds_read_b128 v[202:205], v154
	ds_read_b128 v[206:209], v155
	v_mov_b32_e32 v188, s84
	v_lshl_add_u32 v188, v216, 4, v188
	v_lshrrev_b32_e32 v146, 4, v188
	v_xor_b32_e32 v146, v146, v188
	v_and_b32_e32 v146, 15, v146
	v_lshlrev_b32_e32 v147, 8, v188
	v_or_b32_e32 v148, 0, v217
	v_xor_b32_e32 v148, v148, v146
	v_lshl_add_u32 v190, v148, 4, v147
	v_or_b32_e32 v148, 4, v217
	v_xor_b32_e32 v148, v148, v146
	v_lshl_add_u32 v191, v148, 4, v147
	v_or_b32_e32 v148, 8, v217
	v_xor_b32_e32 v148, v148, v146
	v_lshl_add_u32 v192, v148, 4, v147
	v_or_b32_e32 v148, 12, v217
	v_xor_b32_e32 v148, v148, v146
	v_lshl_add_u32 v193, v148, 4, v147
	v_lshlrev_b32_e32 v194, 3, v188
	v_add_u32_e32 v194, 0x10000, v194
	ds_read_b64 v[144:145], v194
	ds_read_b128 v[128:131], v190
	ds_read_b128 v[132:135], v191
	ds_read_b128 v[136:139], v192
	ds_read_b128 v[140:143], v193
	s_ashr_i32 s77, s76, 4
	s_sub_i32 s77, 64, s77
	s_sub_i32 s78, s40, s76
	s_waitcnt lgkmcnt(0)
	s_add_i32 s93, s8, 0x100
	s_mov_b32 m0, s12
	v_add_u32_e32 v164, s93, v231
	v_med3_i32 v164, v164, 0, s40
	v_lshl_or_b32 v164, v164, 7, v220
	global_load_lds_dwordx4 v164, s[20:21]
	s_add_i32 m0, s12, 0x400
	v_add_u32_e32 v165, s93, v232
	v_med3_i32 v165, v165, 0, s40
	v_lshl_or_b32 v165, v165, 7, v221
	global_load_lds_dwordx4 v165, s[20:21]
	s_waitcnt vmcnt(8)
	v_add_u32_e32 v154, s13, v223
	v_add_u32_e32 v155, s13, v224
	ds_read_b128 v[88:91], v154
	ds_read_b128 v[92:95], v155
	v_mfma_f32_16x16x32_bf16 v[36:39], v[202:205], v[80:83], 0
	v_mfma_f32_16x16x32_bf16 v[36:39], v[206:209], v[84:87], v[36:39]
	s_ashr_i32 s78, s78, 4
	s_add_i32 s78, s78, 64
	v_cndmask_b32_e64 v0, v0, v230, s[52:53]
	v_cndmask_b32_e64 v32, v32, v230, s[62:63]
	v_cndmask_b32_e64 v1, v1, v230, s[56:57]
	v_cndmask_b32_e64 v33, v33, v230, s[64:65]
	v_cndmask_b32_e64 v2, v2, v230, s[58:59]
	v_cndmask_b32_e64 v34, v34, v230, s[70:71]
	v_cndmask_b32_e64 v3, v3, v230, s[60:61]
	v_cndmask_b32_e64 v35, v35, v230, s[72:73]
	v_sub_u32_e32 v200, s77, v229
	s_sub_i32 s91, s78, s77
	v_sub_u32_e32 v150, 0, v200
	v_sub_u32_e32 v151, 1, v200
	v_sub_u32_e32 v152, 2, v200
	v_sub_u32_e32 v153, 3, v200
	v_cmp_lt_u32_e64 s[94:95], s91, v150
	v_cmp_lt_u32_e64 s[86:87], s91, v151
	v_cmp_lt_u32_e64 s[0:1], s91, v152
	v_cmp_lt_u32_e64 s[2:3], s91, v153
	v_cndmask_b32_e64 v0, v0, v230, s[94:95]
	v_cndmask_b32_e64 v1, v1, v230, s[86:87]
	v_cndmask_b32_e64 v2, v2, v230, s[0:1]
	v_cndmask_b32_e64 v3, v3, v230, s[2:3]
	v_sub_u32_e32 v150, 16, v200
	v_sub_u32_e32 v151, 17, v200
	v_sub_u32_e32 v152, 18, v200
	v_sub_u32_e32 v153, 19, v200
	s_waitcnt lgkmcnt(0)
	s_add_i32 s93, s8, 0x200
	s_mov_b32 m0, s13
	v_add_u32_e32 v164, s93, v231
	v_med3_i32 v164, v164, 0, s40
	v_lshl_or_b32 v164, v164, 7, v220
	global_load_lds_dwordx4 v164, s[20:21]
	s_add_i32 m0, s13, 0x400
	v_add_u32_e32 v165, s93, v232
	v_med3_i32 v165, v165, 0, s40
	v_lshl_or_b32 v165, v165, 7, v221
	global_load_lds_dwordx4 v165, s[20:21]
	s_waitcnt vmcnt(8)
	v_add_u32_e32 v154, s14, v223
	v_add_u32_e32 v155, s14, v224
	ds_read_b128 v[202:205], v154
	ds_read_b128 v[206:209], v155
	v_mfma_f32_16x16x32_bf16 v[40:43], v[88:91], v[80:83], 0
	v_mfma_f32_16x16x32_bf16 v[40:43], v[92:95], v[84:87], v[40:43]
	v_cmp_lt_u32_e64 s[94:95], s91, v150
	v_cmp_lt_u32_e64 s[86:87], s91, v151
	v_cmp_lt_u32_e64 s[0:1], s91, v152
	v_cmp_lt_u32_e64 s[2:3], s91, v153
	v_cndmask_b32_e64 v4, v4, v230, s[94:95]
	v_cndmask_b32_e64 v5, v5, v230, s[86:87]
	v_cndmask_b32_e64 v6, v6, v230, s[0:1]
	v_cndmask_b32_e64 v7, v7, v230, s[2:3]
	v_sub_u32_e32 v150, 32, v200
	v_sub_u32_e32 v151, 33, v200
	v_sub_u32_e32 v152, 34, v200
	v_sub_u32_e32 v153, 35, v200
	v_cmp_lt_u32_e64 s[94:95], s91, v150
	v_cmp_lt_u32_e64 s[86:87], s91, v151
	v_cmp_lt_u32_e64 s[0:1], s91, v152
	v_cmp_lt_u32_e64 s[2:3], s91, v153
	v_cndmask_b32_e64 v8, v8, v230, s[94:95]
	v_cndmask_b32_e64 v9, v9, v230, s[86:87]
	v_cndmask_b32_e64 v10, v10, v230, s[0:1]
	v_cndmask_b32_e64 v11, v11, v230, s[2:3]
	v_sub_u32_e32 v150, 48, v200
	v_sub_u32_e32 v151, 49, v200
	v_sub_u32_e32 v152, 50, v200
	v_sub_u32_e32 v153, 51, v200
	v_cmp_lt_u32_e64 s[94:95], s91, v150
	v_cmp_lt_u32_e64 s[86:87], s91, v151
	v_cmp_lt_u32_e64 s[0:1], s91, v152
	v_cmp_lt_u32_e64 s[2:3], s91, v153
	s_waitcnt lgkmcnt(0)
	s_add_i32 s93, s8, 0x300
	s_mov_b32 m0, s14
	v_add_u32_e32 v164, s93, v231
	v_med3_i32 v164, v164, 0, s40
	v_lshl_or_b32 v164, v164, 7, v220
	global_load_lds_dwordx4 v164, s[20:21]
	s_add_i32 m0, s14, 0x400
	v_add_u32_e32 v165, s93, v232
	v_med3_i32 v165, v165, 0, s40
	v_lshl_or_b32 v165, v165, 7, v221
	global_load_lds_dwordx4 v165, s[20:21]
	s_waitcnt vmcnt(8)
	v_add_u32_e32 v154, s15, v223
	v_add_u32_e32 v155, s15, v224
	ds_read_b128 v[88:91], v154
	ds_read_b128 v[92:95], v155
	v_mfma_f32_16x16x32_bf16 v[44:47], v[202:205], v[80:83], 0
	v_mfma_f32_16x16x32_bf16 v[44:47], v[206:209], v[84:87], v[44:47]
	v_cndmask_b32_e64 v12, v12, v230, s[94:95]
	v_cndmask_b32_e64 v13, v13, v230, s[86:87]
	v_cndmask_b32_e64 v14, v14, v230, s[0:1]
	v_cndmask_b32_e64 v15, v15, v230, s[2:3]
	v_sub_u32_e32 v150, 64, v200
	v_sub_u32_e32 v151, 0x41, v200
	v_sub_u32_e32 v152, 0x42, v200
	v_sub_u32_e32 v153, 0x43, v200
	v_cmp_lt_u32_e64 s[94:95], s91, v150
	v_cmp_lt_u32_e64 s[86:87], s91, v151
	v_cmp_lt_u32_e64 s[0:1], s91, v152
	v_cmp_lt_u32_e64 s[2:3], s91, v153
	v_cndmask_b32_e64 v16, v16, v230, s[94:95]
	v_cndmask_b32_e64 v17, v17, v230, s[86:87]
	v_cndmask_b32_e64 v18, v18, v230, s[0:1]
	v_cndmask_b32_e64 v19, v19, v230, s[2:3]
	v_sub_u32_e32 v150, 0x50, v200
	v_sub_u32_e32 v151, 0x51, v200
	v_sub_u32_e32 v152, 0x52, v200
	v_sub_u32_e32 v153, 0x53, v200
	v_cmp_lt_u32_e64 s[94:95], s91, v150
	v_cmp_lt_u32_e64 s[86:87], s91, v151
	v_cmp_lt_u32_e64 s[0:1], s91, v152
	v_cmp_lt_u32_e64 s[2:3], s91, v153
	v_cndmask_b32_e64 v20, v20, v230, s[94:95]
	v_cndmask_b32_e64 v21, v21, v230, s[86:87]
	v_cndmask_b32_e64 v22, v22, v230, s[0:1]
	v_cndmask_b32_e64 v23, v23, v230, s[2:3]
	s_waitcnt lgkmcnt(0)
	s_add_i32 s93, s8, 0x400
	s_mov_b32 m0, s15
	v_add_u32_e32 v164, s93, v231
	v_med3_i32 v164, v164, 0, s40
	v_lshl_or_b32 v164, v164, 7, v220
	global_load_lds_dwordx4 v164, s[20:21]
	s_add_i32 m0, s15, 0x400
	v_add_u32_e32 v165, s93, v232
	v_med3_i32 v165, v165, 0, s40
	v_lshl_or_b32 v165, v165, 7, v221
	global_load_lds_dwordx4 v165, s[20:21]
	s_waitcnt vmcnt(8)
	v_add_u32_e32 v154, s16, v223
	v_add_u32_e32 v155, s16, v224
	ds_read_b128 v[202:205], v154
	ds_read_b128 v[206:209], v155
	v_mfma_f32_16x16x32_bf16 v[48:51], v[88:91], v[80:83], 0
	v_mfma_f32_16x16x32_bf16 v[48:51], v[92:95], v[84:87], v[48:51]
	v_sub_u32_e32 v150, 0x60, v200
	v_sub_u32_e32 v151, 0x61, v200
	v_sub_u32_e32 v152, 0x62, v200
	v_sub_u32_e32 v153, 0x63, v200
	v_cmp_lt_u32_e64 s[94:95], s91, v150
	v_cmp_lt_u32_e64 s[86:87], s91, v151
	v_cmp_lt_u32_e64 s[0:1], s91, v152
	v_cmp_lt_u32_e64 s[2:3], s91, v153
	v_cndmask_b32_e64 v24, v24, v230, s[94:95]
	v_cndmask_b32_e64 v25, v25, v230, s[86:87]
	v_cndmask_b32_e64 v26, v26, v230, s[0:1]
	v_cndmask_b32_e64 v27, v27, v230, s[2:3]
	v_sub_u32_e32 v150, 0x70, v200
	v_sub_u32_e32 v151, 0x71, v200
	v_sub_u32_e32 v152, 0x72, v200
	v_sub_u32_e32 v153, 0x73, v200
	v_cmp_lt_u32_e64 s[94:95], s91, v150
	v_cmp_lt_u32_e64 s[86:87], s91, v151
	v_cmp_lt_u32_e64 s[0:1], s91, v152
	v_cmp_lt_u32_e64 s[2:3], s91, v153
	v_cndmask_b32_e64 v28, v28, v230, s[94:95]
	v_cndmask_b32_e64 v29, v29, v230, s[86:87]
	v_cndmask_b32_e64 v30, v30, v230, s[0:1]
	v_cndmask_b32_e64 v31, v31, v230, s[2:3]
	v_sub_u32_e32 v150, 0x80, v200
	v_sub_u32_e32 v151, 0x81, v200
	v_sub_u32_e32 v152, 0x82, v200
	v_sub_u32_e32 v153, 0x83, v200
	s_waitcnt lgkmcnt(0)
	s_add_i32 s93, s76, 0xfffffc00
	s_mov_b32 m0, s16
	v_add_u32_e32 v164, s93, v231
	v_med3_i32 v164, v164, 0, s40
	v_lshl_or_b32 v164, v164, 7, v222
	global_load_lds_dwordx4 v164, s[24:25]
	s_add_i32 m0, s16, 0x400
	v_add_u32_e32 v165, s93, v232
	v_med3_i32 v165, v165, 0, s40
	v_lshl_or_b32 v165, v165, 7, v222
	global_load_lds_dwordx4 v165, s[24:25]
	s_waitcnt vmcnt(8)
	v_add_u32_e32 v154, s12, v223
	v_add_u32_e32 v155, s12, v224
	ds_read_b128 v[88:91], v154
	ds_read_b128 v[92:95], v155
	v_mfma_f32_16x16x32_bf16 v[52:55], v[202:205], v[80:83], 0
	v_mfma_f32_16x16x32_bf16 v[52:55], v[206:209], v[84:87], v[52:55]
	v_cmp_lt_u32_e64 s[94:95], s91, v150
	v_cmp_lt_u32_e64 s[86:87], s91, v151
	v_cmp_lt_u32_e64 s[0:1], s91, v152
	v_cmp_lt_u32_e64 s[2:3], s91, v153
	v_cndmask_b32_e64 v32, v32, v230, s[94:95]
	v_cndmask_b32_e64 v33, v33, v230, s[86:87]
	v_cndmask_b32_e64 v34, v34, v230, s[0:1]
	v_cndmask_b32_e64 v35, v35, v230, s[2:3]
	v_max3_f32 v184, v0, v1, v2
	v_max3_f32 v184, v184, v3, v4
	v_max3_f32 v184, v184, v5, v6
	v_max3_f32 v184, v184, v7, v8
	v_max3_f32 v184, v184, v9, v10
	v_max3_f32 v184, v184, v11, v12
	v_max3_f32 v184, v184, v13, v14
	v_max3_f32 v184, v184, v15, v16
	v_max3_f32 v184, v184, v17, v18
	v_max3_f32 v184, v184, v19, v20
	v_max3_f32 v184, v184, v21, v22
	v_max3_f32 v184, v184, v23, v24
	v_max3_f32 v184, v184, v25, v26
	v_max3_f32 v184, v184, v27, v28
	v_max3_f32 v184, v184, v29, v30
	v_max3_f32 v184, v184, v31, v32
	v_max3_f32 v184, v184, v33, v34
	v_max_f32_e32 v184, v184, v35
	v_mov_b32_e32 v146, v184
	s_nop 1
	v_permlane16_swap_b32_e32 v184, v146
	s_waitcnt lgkmcnt(0)
	s_add_i32 s93, s76, 0xfffffd00
	s_mov_b32 m0, s12
	v_add_u32_e32 v164, s93, v231
	v_med3_i32 v164, v164, 0, s40
	v_lshl_or_b32 v164, v164, 7, v222
	global_load_lds_dwordx4 v164, s[24:25]
	s_add_i32 m0, s12, 0x400
	v_add_u32_e32 v165, s93, v232
	v_med3_i32 v165, v165, 0, s40
	v_lshl_or_b32 v165, v165, 7, v222
	global_load_lds_dwordx4 v165, s[24:25]
	s_waitcnt vmcnt(8)
	v_add_u32_e32 v154, s13, v223
	v_add_u32_e32 v155, s13, v224
	ds_read_b128 v[202:205], v154
	ds_read_b128 v[206:209], v155
	v_mfma_f32_16x16x32_bf16 v[56:59], v[88:91], v[80:83], 0
	v_mfma_f32_16x16x32_bf16 v[56:59], v[92:95], v[84:87], v[56:59]
	v_max_f32_e32 v184, v184, v146
	v_mov_b32_e32 v146, v184
	s_nop 1
	v_permlane32_swap_b32_e32 v184, v146
	v_max_f32_e32 v184, v184, v146
	v_pk_add_f32 v[0:1], v[0:1], v[184:185] op_sel_hi:[1,0] neg_lo:[0,1] neg_hi:[0,1]
	v_pk_add_f32 v[2:3], v[2:3], v[184:185] op_sel_hi:[1,0] neg_lo:[0,1] neg_hi:[0,1]
	v_pk_add_f32 v[4:5], v[4:5], v[184:185] op_sel_hi:[1,0] neg_lo:[0,1] neg_hi:[0,1]
	v_pk_add_f32 v[6:7], v[6:7], v[184:185] op_sel_hi:[1,0] neg_lo:[0,1] neg_hi:[0,1]
	v_exp_f32_e32 v0, v0
	v_exp_f32_e32 v1, v1
	v_exp_f32_e32 v2, v2
	v_exp_f32_e32 v3, v3
	v_pk_add_f32 v[8:9], v[8:9], v[184:185] op_sel_hi:[1,0] neg_lo:[0,1] neg_hi:[0,1]
	v_pk_add_f32 v[10:11], v[10:11], v[184:185] op_sel_hi:[1,0] neg_lo:[0,1] neg_hi:[0,1]
	v_exp_f32_e32 v4, v4
	v_exp_f32_e32 v5, v5
	v_exp_f32_e32 v6, v6
	v_exp_f32_e32 v7, v7
	v_pk_add_f32 v[12:13], v[12:13], v[184:185] op_sel_hi:[1,0] neg_lo:[0,1] neg_hi:[0,1]
	v_pk_add_f32 v[14:15], v[14:15], v[184:185] op_sel_hi:[1,0] neg_lo:[0,1] neg_hi:[0,1]
	v_exp_f32_e32 v8, v8
	v_exp_f32_e32 v9, v9
	v_exp_f32_e32 v10, v10
	v_exp_f32_e32 v11, v11
	v_pk_add_f32 v[16:17], v[16:17], v[184:185] op_sel_hi:[1,0] neg_lo:[0,1] neg_hi:[0,1]
	v_pk_add_f32 v[18:19], v[18:19], v[184:185] op_sel_hi:[1,0] neg_lo:[0,1] neg_hi:[0,1]
	v_exp_f32_e32 v12, v12
	v_exp_f32_e32 v13, v13
	s_waitcnt lgkmcnt(0)
	s_add_i32 s93, s76, 0xfffffe00
	s_mov_b32 m0, s13
	v_add_u32_e32 v164, s93, v231
	v_med3_i32 v164, v164, 0, s40
	v_lshl_or_b32 v164, v164, 7, v222
	global_load_lds_dwordx4 v164, s[24:25]
	s_add_i32 m0, s13, 0x400
	v_add_u32_e32 v165, s93, v232
	v_med3_i32 v165, v165, 0, s40
	v_lshl_or_b32 v165, v165, 7, v222
	global_load_lds_dwordx4 v165, s[24:25]
	s_waitcnt vmcnt(8)
	v_add_u32_e32 v154, s14, v223
	v_add_u32_e32 v155, s14, v224
	ds_read_b128 v[88:91], v154
	ds_read_b128 v[92:95], v155
	v_mfma_f32_16x16x32_bf16 v[60:63], v[202:205], v[80:83], 0
	v_mfma_f32_16x16x32_bf16 v[60:63], v[206:209], v[84:87], v[60:63]
	v_exp_f32_e32 v14, v14
	v_exp_f32_e32 v15, v15
	v_pk_add_f32 v[20:21], v[20:21], v[184:185] op_sel_hi:[1,0] neg_lo:[0,1] neg_hi:[0,1]
	v_pk_add_f32 v[22:23], v[22:23], v[184:185] op_sel_hi:[1,0] neg_lo:[0,1] neg_hi:[0,1]
	v_exp_f32_e32 v16, v16
	v_exp_f32_e32 v17, v17
	v_exp_f32_e32 v18, v18
	v_exp_f32_e32 v19, v19
	v_pk_add_f32 v[24:25], v[24:25], v[184:185] op_sel_hi:[1,0] neg_lo:[0,1] neg_hi:[0,1]
	v_pk_add_f32 v[26:27], v[26:27], v[184:185] op_sel_hi:[1,0] neg_lo:[0,1] neg_hi:[0,1]
	v_exp_f32_e32 v20, v20
	v_exp_f32_e32 v21, v21
	v_exp_f32_e32 v22, v22
	v_exp_f32_e32 v23, v23
	v_pk_add_f32 v[28:29], v[28:29], v[184:185] op_sel_hi:[1,0] neg_lo:[0,1] neg_hi:[0,1]
	v_pk_add_f32 v[30:31], v[30:31], v[184:185] op_sel_hi:[1,0] neg_lo:[0,1] neg_hi:[0,1]
	v_exp_f32_e32 v24, v24
	v_exp_f32_e32 v25, v25
	v_exp_f32_e32 v26, v26
	v_exp_f32_e32 v27, v27
	v_pk_add_f32 v[32:33], v[32:33], v[184:185] op_sel_hi:[1,0] neg_lo:[0,1] neg_hi:[0,1]
	v_pk_add_f32 v[34:35], v[34:35], v[184:185] op_sel_hi:[1,0] neg_lo:[0,1] neg_hi:[0,1]
	v_exp_f32_e32 v28, v28
	v_exp_f32_e32 v29, v29
	v_exp_f32_e32 v30, v30
	v_exp_f32_e32 v31, v31
	v_exp_f32_e32 v32, v32
	v_exp_f32_e32 v33, v33
	s_waitcnt lgkmcnt(0)
	s_add_i32 s93, s76, 0xffffff00
	s_mov_b32 m0, s14
	v_add_u32_e32 v164, s93, v231
	v_med3_i32 v164, v164, 0, s40
	v_lshl_or_b32 v164, v164, 7, v222
	global_load_lds_dwordx4 v164, s[24:25]
	s_add_i32 m0, s14, 0x400
	v_add_u32_e32 v165, s93, v232
	v_med3_i32 v165, v165, 0, s40
	v_lshl_or_b32 v165, v165, 7, v222
	global_load_lds_dwordx4 v165, s[24:25]
	s_waitcnt vmcnt(8)
	v_add_u32_e32 v154, s15, v223
	v_add_u32_e32 v155, s15, v224
	ds_read_b128 v[202:205], v154
	ds_read_b128 v[206:209], v155
	v_mfma_f32_16x16x32_bf16 v[64:67], v[88:91], v[80:83], 0
	v_mfma_f32_16x16x32_bf16 v[64:67], v[92:95], v[84:87], v[64:67]
	v_exp_f32_e32 v34, v34
	v_exp_f32_e32 v35, v35
	s_nop 0
	v_pk_add_f32 v[146:147], v[0:1], v[2:3]
	v_pk_add_f32 v[148:149], v[4:5], v[6:7]
	v_pk_add_f32 v[146:147], v[146:147], v[8:9]
	v_pk_add_f32 v[148:149], v[148:149], v[10:11]
	v_pk_add_f32 v[146:147], v[146:147], v[12:13]
	v_pk_add_f32 v[148:149], v[148:149], v[14:15]
	v_pk_add_f32 v[146:147], v[146:147], v[16:17]
	v_pk_add_f32 v[148:149], v[148:149], v[18:19]
	v_pk_add_f32 v[146:147], v[146:147], v[20:21]
	v_pk_add_f32 v[148:149], v[148:149], v[22:23]
	v_pk_add_f32 v[146:147], v[146:147], v[24:25]
	v_pk_add_f32 v[148:149], v[148:149], v[26:27]
	v_pk_add_f32 v[146:147], v[146:147], v[28:29]
	v_pk_add_f32 v[148:149], v[148:149], v[30:31]
	v_pk_add_f32 v[146:147], v[146:147], v[32:33]
	v_pk_add_f32 v[148:149], v[148:149], v[34:35]
	s_nop 0
	v_pk_add_f32 v[146:147], v[146:147], v[148:149]
	s_nop 0
	v_add_f32_e32 v185, v146, v147
	v_cvt_pk_bf16_f32 v0, v0, v1
	v_cvt_pk_bf16_f32 v1, v2, v3
	v_cvt_pk_bf16_f32 v4, v4, v5
	v_cvt_pk_bf16_f32 v5, v6, v7
	v_cvt_pk_bf16_f32 v8, v8, v9
	s_waitcnt lgkmcnt(0)
	s_add_i32 s93, s76, 0
	s_mov_b32 m0, s15
	v_add_u32_e32 v164, s93, v231
	v_med3_i32 v164, v164, 0, s40
	v_lshl_or_b32 v164, v164, 7, v222
	global_load_lds_dwordx4 v164, s[24:25]
	s_add_i32 m0, s15, 0x400
	v_add_u32_e32 v165, s93, v232
	v_med3_i32 v165, v165, 0, s40
	v_lshl_or_b32 v165, v165, 7, v222
	global_load_lds_dwordx4 v165, s[24:25]
	s_waitcnt vmcnt(8)
	v_add_u32_e32 v154, s16, v225
	v_add_u32_e32 v155, s16, v226
	v_add_u32_e32 v156, s16, v227
	v_add_u32_e32 v157, s16, v228
	ds_read_b64_tr_b16 v[88:89], v154
	ds_read_b64_tr_b16 v[90:91], v155
	ds_read_b64_tr_b16 v[92:93], v156
	ds_read_b64_tr_b16 v[94:95], v157
	v_mfma_f32_16x16x32_bf16 v[68:71], v[202:205], v[80:83], 0
	v_mfma_f32_16x16x32_bf16 v[68:71], v[206:209], v[84:87], v[68:71]
	v_cvt_pk_bf16_f32 v9, v10, v11
	v_cvt_pk_bf16_f32 v12, v12, v13
	v_cvt_pk_bf16_f32 v13, v14, v15
	v_cvt_pk_bf16_f32 v16, v16, v17
	v_cvt_pk_bf16_f32 v17, v18, v19
	v_cvt_pk_bf16_f32 v20, v20, v21
	v_cvt_pk_bf16_f32 v21, v22, v23
	v_cvt_pk_bf16_f32 v24, v24, v25
	v_cvt_pk_bf16_f32 v25, v26, v27
	v_cvt_pk_bf16_f32 v28, v28, v29
	v_cvt_pk_bf16_f32 v29, v30, v31
	v_cvt_pk_bf16_f32 v32, v32, v33
	v_cvt_pk_bf16_f32 v33, v34, v35
	v_mov_b32_e32 v146, v185
	s_nop 1
	v_permlane16_swap_b32_e32 v185, v146
	v_add_f32_e32 v185, v185, v146
	v_mov_b32_e32 v146, v185
	s_nop 1
	v_permlane32_swap_b32_e32 v185, v146
	v_add_f32_e32 v185, v185, v146
	s_waitcnt lgkmcnt(0)
	s_add_i32 s93, s76, 0x100
	s_mov_b32 m0, s16
	v_add_u32_e32 v164, s93, v231
	v_med3_i32 v164, v164, 0, s40
	v_lshl_or_b32 v164, v164, 7, v222
	global_load_lds_dwordx4 v164, s[24:25]
	s_add_i32 m0, s16, 0x400
	v_add_u32_e32 v165, s93, v232
	v_med3_i32 v165, v165, 0, s40
	v_lshl_or_b32 v165, v165, 7, v222
	global_load_lds_dwordx4 v165, s[24:25]
	s_waitcnt vmcnt(8)
	v_add_u32_e32 v154, s12, v225
	v_add_u32_e32 v155, s12, v226
	v_add_u32_e32 v156, s12, v227
	v_add_u32_e32 v157, s12, v228
	ds_read_b64_tr_b16 v[202:203], v154
	ds_read_b64_tr_b16 v[204:205], v155
	ds_read_b64_tr_b16 v[206:207], v156
	ds_read_b64_tr_b16 v[208:209], v157
	v_mfma_f32_16x16x16_bf16 v[96:99], v[88:89], v[0:1], 0
	v_mfma_f32_16x16x16_bf16 v[100:103], v[90:91], v[0:1], 0
	v_mfma_f32_16x16x16_bf16 v[104:107], v[92:93], v[0:1], 0
	v_mfma_f32_16x16x16_bf16 v[108:111], v[94:95], v[0:1], 0
	v_mov_b32_e32 v189, s85
	v_lshl_add_u32 v189, v216, 4, v189
	v_lshrrev_b32_e32 v146, 4, v189
	v_xor_b32_e32 v146, v146, v189
	v_and_b32_e32 v146, 15, v146
	v_lshlrev_b32_e32 v147, 8, v189
	v_or_b32_e32 v148, 0, v217
	v_xor_b32_e32 v148, v148, v146
	v_lshl_add_u32 v195, v148, 4, v147
	v_or_b32_e32 v148, 4, v217
	v_xor_b32_e32 v148, v148, v146
	v_lshl_add_u32 v196, v148, 4, v147
	v_or_b32_e32 v148, 8, v217
	v_xor_b32_e32 v148, v148, v146
	v_lshl_add_u32 v197, v148, 4, v147
	v_or_b32_e32 v148, 12, v217
	v_xor_b32_e32 v148, v148, v146
	v_lshl_add_u32 v198, v148, 4, v147
	v_lshlrev_b32_e32 v199, 3, v189
	v_add_u32_e32 v199, 0x10000, v199
	ds_read_b64 v[182:183], v199
	ds_read_b128 v[166:169], v195
	ds_read_b128 v[170:173], v196
	ds_read_b128 v[174:177], v197
	ds_read_b128 v[178:181], v198
	s_ashr_i32 s77, s8, 4
	s_sub_i32 s77, 64, s77
	s_sub_i32 s78, s40, s8
	s_ashr_i32 s78, s78, 4
	s_add_i32 s78, s78, 64
	v_cndmask_b32_e64 v36, v36, v230, s[52:53]
	s_waitcnt lgkmcnt(0)
	s_add_i32 s93, s76, 0x200
	s_mov_b32 m0, s12
	v_add_u32_e32 v164, s93, v231
	v_med3_i32 v164, v164, 0, s40
	v_lshl_or_b32 v164, v164, 7, v222
	global_load_lds_dwordx4 v164, s[24:25]
	s_add_i32 m0, s12, 0x400
	v_add_u32_e32 v165, s93, v232
	v_med3_i32 v165, v165, 0, s40
	v_lshl_or_b32 v165, v165, 7, v222
	global_load_lds_dwordx4 v165, s[24:25]
	s_waitcnt vmcnt(8)
	v_add_u32_e32 v154, s13, v225
	v_add_u32_e32 v155, s13, v226
	v_add_u32_e32 v156, s13, v227
	v_add_u32_e32 v157, s13, v228
	ds_read_b64_tr_b16 v[88:89], v154
	ds_read_b64_tr_b16 v[90:91], v155
	ds_read_b64_tr_b16 v[92:93], v156
	ds_read_b64_tr_b16 v[94:95], v157
	v_mfma_f32_16x16x16_bf16 v[96:99], v[202:203], v[4:5], v[96:99]
	v_mfma_f32_16x16x16_bf16 v[100:103], v[204:205], v[4:5], v[100:103]
	v_mfma_f32_16x16x16_bf16 v[104:107], v[206:207], v[4:5], v[104:107]
	v_mfma_f32_16x16x16_bf16 v[108:111], v[208:209], v[4:5], v[108:111]
	v_cndmask_b32_e64 v68, v68, v230, s[62:63]
	v_cndmask_b32_e64 v37, v37, v230, s[56:57]
	v_cndmask_b32_e64 v69, v69, v230, s[64:65]
	v_cndmask_b32_e64 v38, v38, v230, s[58:59]
	v_cndmask_b32_e64 v70, v70, v230, s[70:71]
	v_cndmask_b32_e64 v39, v39, v230, s[60:61]
	v_cndmask_b32_e64 v71, v71, v230, s[72:73]
	v_sub_u32_e32 v200, s77, v229
	s_sub_i32 s91, s78, s77
	v_sub_u32_e32 v150, 0, v200
	v_sub_u32_e32 v151, 1, v200
	v_sub_u32_e32 v152, 2, v200
	v_sub_u32_e32 v153, 3, v200
	v_cmp_lt_u32_e64 s[94:95], s91, v150
	v_cmp_lt_u32_e64 s[86:87], s91, v151
	v_cmp_lt_u32_e64 s[0:1], s91, v152
	v_cmp_lt_u32_e64 s[2:3], s91, v153
	v_cndmask_b32_e64 v36, v36, v230, s[94:95]
	v_cndmask_b32_e64 v37, v37, v230, s[86:87]
	v_cndmask_b32_e64 v38, v38, v230, s[0:1]
	v_cndmask_b32_e64 v39, v39, v230, s[2:3]
	v_sub_u32_e32 v150, 16, v200
	v_sub_u32_e32 v151, 17, v200
	v_sub_u32_e32 v152, 18, v200
	v_sub_u32_e32 v153, 19, v200
	v_cmp_lt_u32_e64 s[94:95], s91, v150
	v_cmp_lt_u32_e64 s[86:87], s91, v151
	v_cmp_lt_u32_e64 s[0:1], s91, v152
	v_cmp_lt_u32_e64 s[2:3], s91, v153
	v_cndmask_b32_e64 v40, v40, v230, s[94:95]
	v_cndmask_b32_e64 v41, v41, v230, s[86:87]
	s_waitcnt lgkmcnt(0)
	s_add_i32 s93, s76, 0x300
	s_mov_b32 m0, s13
	v_add_u32_e32 v164, s93, v231
	v_med3_i32 v164, v164, 0, s40
	v_lshl_or_b32 v164, v164, 7, v222
	global_load_lds_dwordx4 v164, s[24:25]
	s_add_i32 m0, s13, 0x400
	v_add_u32_e32 v165, s93, v232
	v_med3_i32 v165, v165, 0, s40
	v_lshl_or_b32 v165, v165, 7, v222
	global_load_lds_dwordx4 v165, s[24:25]
	s_waitcnt vmcnt(8)
	v_add_u32_e32 v154, s14, v225
	v_add_u32_e32 v155, s14, v226
	v_add_u32_e32 v156, s14, v227
	v_add_u32_e32 v157, s14, v228
	ds_read_b64_tr_b16 v[202:203], v154
	ds_read_b64_tr_b16 v[204:205], v155
	ds_read_b64_tr_b16 v[206:207], v156
	ds_read_b64_tr_b16 v[208:209], v157
	v_mfma_f32_16x16x16_bf16 v[96:99], v[88:89], v[8:9], v[96:99]
	v_mfma_f32_16x16x16_bf16 v[100:103], v[90:91], v[8:9], v[100:103]
	v_mfma_f32_16x16x16_bf16 v[104:107], v[92:93], v[8:9], v[104:107]
	v_mfma_f32_16x16x16_bf16 v[108:111], v[94:95], v[8:9], v[108:111]
	v_cndmask_b32_e64 v42, v42, v230, s[0:1]
	v_cndmask_b32_e64 v43, v43, v230, s[2:3]
	v_sub_u32_e32 v150, 32, v200
	v_sub_u32_e32 v151, 33, v200
	v_sub_u32_e32 v152, 34, v200
	v_sub_u32_e32 v153, 35, v200
	v_cmp_lt_u32_e64 s[94:95], s91, v150
	v_cmp_lt_u32_e64 s[86:87], s91, v151
	v_cmp_lt_u32_e64 s[0:1], s91, v152
	v_cmp_lt_u32_e64 s[2:3], s91, v153
	v_cndmask_b32_e64 v44, v44, v230, s[94:95]
	v_cndmask_b32_e64 v45, v45, v230, s[86:87]
	v_cndmask_b32_e64 v46, v46, v230, s[0:1]
	v_cndmask_b32_e64 v47, v47, v230, s[2:3]
	v_sub_u32_e32 v150, 48, v200
	v_sub_u32_e32 v151, 49, v200
	v_sub_u32_e32 v152, 50, v200
	v_sub_u32_e32 v153, 51, v200
	v_cmp_lt_u32_e64 s[94:95], s91, v150
	v_cmp_lt_u32_e64 s[86:87], s91, v151
	v_cmp_lt_u32_e64 s[0:1], s91, v152
	v_cmp_lt_u32_e64 s[2:3], s91, v153
	v_cndmask_b32_e64 v48, v48, v230, s[94:95]
	v_cndmask_b32_e64 v49, v49, v230, s[86:87]
	v_cndmask_b32_e64 v50, v50, v230, s[0:1]
	v_cndmask_b32_e64 v51, v51, v230, s[2:3]
	v_sub_u32_e32 v150, 64, v200
	v_sub_u32_e32 v151, 0x41, v200
	v_sub_u32_e32 v152, 0x42, v200
	v_sub_u32_e32 v153, 0x43, v200
	v_cmp_lt_u32_e64 s[94:95], s91, v150
	s_waitcnt lgkmcnt(0)
	s_add_i32 s93, s76, 0x400
	s_mov_b32 m0, s14
	v_add_u32_e32 v164, s93, v231
	v_med3_i32 v164, v164, 0, s40
	v_lshl_or_b32 v164, v164, 7, v222
	global_load_lds_dwordx4 v164, s[24:25]
	s_add_i32 m0, s14, 0x400
	v_add_u32_e32 v165, s93, v232
	v_med3_i32 v165, v165, 0, s40
	v_lshl_or_b32 v165, v165, 7, v222
	global_load_lds_dwordx4 v165, s[24:25]
	s_waitcnt vmcnt(8)
	v_add_u32_e32 v154, s15, v225
	v_add_u32_e32 v155, s15, v226
	v_add_u32_e32 v156, s15, v227
	v_add_u32_e32 v157, s15, v228
	ds_read_b64_tr_b16 v[88:89], v154
	ds_read_b64_tr_b16 v[90:91], v155
	ds_read_b64_tr_b16 v[92:93], v156
	ds_read_b64_tr_b16 v[94:95], v157
	v_mfma_f32_16x16x16_bf16 v[96:99], v[202:203], v[12:13], v[96:99]
	v_mfma_f32_16x16x16_bf16 v[100:103], v[204:205], v[12:13], v[100:103]
	v_mfma_f32_16x16x16_bf16 v[104:107], v[206:207], v[12:13], v[104:107]
	v_mfma_f32_16x16x16_bf16 v[108:111], v[208:209], v[12:13], v[108:111]
	v_cmp_lt_u32_e64 s[86:87], s91, v151
	v_cmp_lt_u32_e64 s[0:1], s91, v152
	v_cmp_lt_u32_e64 s[2:3], s91, v153
	v_cndmask_b32_e64 v52, v52, v230, s[94:95]
	v_cndmask_b32_e64 v53, v53, v230, s[86:87]
	v_cndmask_b32_e64 v54, v54, v230, s[0:1]
	v_cndmask_b32_e64 v55, v55, v230, s[2:3]
	v_sub_u32_e32 v150, 0x50, v200
	v_sub_u32_e32 v151, 0x51, v200
	v_sub_u32_e32 v152, 0x52, v200
	v_sub_u32_e32 v153, 0x53, v200
	v_cmp_lt_u32_e64 s[94:95], s91, v150
	v_cmp_lt_u32_e64 s[86:87], s91, v151
	v_cmp_lt_u32_e64 s[0:1], s91, v152
	v_cmp_lt_u32_e64 s[2:3], s91, v153
	v_cndmask_b32_e64 v56, v56, v230, s[94:95]
	v_cndmask_b32_e64 v57, v57, v230, s[86:87]
	v_cndmask_b32_e64 v58, v58, v230, s[0:1]
	v_cndmask_b32_e64 v59, v59, v230, s[2:3]
	v_sub_u32_e32 v150, 0x60, v200
	v_sub_u32_e32 v151, 0x61, v200
	v_sub_u32_e32 v152, 0x62, v200
	v_sub_u32_e32 v153, 0x63, v200
	v_cmp_lt_u32_e64 s[94:95], s91, v150
	v_cmp_lt_u32_e64 s[86:87], s91, v151
	v_cmp_lt_u32_e64 s[0:1], s91, v152
	v_cmp_lt_u32_e64 s[2:3], s91, v153
	v_cndmask_b32_e64 v60, v60, v230, s[94:95]
	v_cndmask_b32_e64 v61, v61, v230, s[86:87]
	v_cndmask_b32_e64 v62, v62, v230, s[0:1]
	v_cndmask_b32_e64 v63, v63, v230, s[2:3]
	s_waitcnt lgkmcnt(0)
	s_add_i32 s93, s8, 0xfffffc00
	s_mov_b32 m0, s15
	v_add_u32_e32 v164, s93, v231
	v_med3_i32 v164, v164, 0, s40
	v_lshl_or_b32 v164, v164, 7, v222
	global_load_lds_dwordx4 v164, s[24:25]
	s_add_i32 m0, s15, 0x400
	v_add_u32_e32 v165, s93, v232
	v_med3_i32 v165, v165, 0, s40
	v_lshl_or_b32 v165, v165, 7, v222
	global_load_lds_dwordx4 v165, s[24:25]
	s_waitcnt vmcnt(8)
	v_add_u32_e32 v154, s16, v225
	v_add_u32_e32 v155, s16, v226
	v_add_u32_e32 v156, s16, v227
	v_add_u32_e32 v157, s16, v228
	ds_read_b64_tr_b16 v[202:203], v154
	ds_read_b64_tr_b16 v[204:205], v155
	ds_read_b64_tr_b16 v[206:207], v156
	ds_read_b64_tr_b16 v[208:209], v157
	v_mfma_f32_16x16x16_bf16 v[96:99], v[88:89], v[16:17], v[96:99]
	v_mfma_f32_16x16x16_bf16 v[100:103], v[90:91], v[16:17], v[100:103]
	v_mfma_f32_16x16x16_bf16 v[104:107], v[92:93], v[16:17], v[104:107]
	v_mfma_f32_16x16x16_bf16 v[108:111], v[94:95], v[16:17], v[108:111]
	v_sub_u32_e32 v150, 0x70, v200
	v_sub_u32_e32 v151, 0x71, v200
	v_sub_u32_e32 v152, 0x72, v200
	v_sub_u32_e32 v153, 0x73, v200
	v_cmp_lt_u32_e64 s[94:95], s91, v150
	v_cmp_lt_u32_e64 s[86:87], s91, v151
	v_cmp_lt_u32_e64 s[0:1], s91, v152
	v_cmp_lt_u32_e64 s[2:3], s91, v153
	v_cndmask_b32_e64 v64, v64, v230, s[94:95]
	v_cndmask_b32_e64 v65, v65, v230, s[86:87]
	v_cndmask_b32_e64 v66, v66, v230, s[0:1]
	v_cndmask_b32_e64 v67, v67, v230, s[2:3]
	v_sub_u32_e32 v150, 0x80, v200
	v_sub_u32_e32 v151, 0x81, v200
	v_sub_u32_e32 v152, 0x82, v200
	v_sub_u32_e32 v153, 0x83, v200
	v_cmp_lt_u32_e64 s[94:95], s91, v150
	v_cmp_lt_u32_e64 s[86:87], s91, v151
	v_cmp_lt_u32_e64 s[0:1], s91, v152
	v_cmp_lt_u32_e64 s[2:3], s91, v153
	v_cndmask_b32_e64 v68, v68, v230, s[94:95]
	v_cndmask_b32_e64 v69, v69, v230, s[86:87]
	v_cndmask_b32_e64 v70, v70, v230, s[0:1]
	v_cndmask_b32_e64 v71, v71, v230, s[2:3]
	v_max3_f32 v186, v36, v37, v38
	v_max3_f32 v186, v186, v39, v40
	v_max3_f32 v186, v186, v41, v42
	v_max3_f32 v186, v186, v43, v44
	v_max3_f32 v186, v186, v45, v46
	v_max3_f32 v186, v186, v47, v48
	v_max3_f32 v186, v186, v49, v50
	s_waitcnt lgkmcnt(0)
	s_add_i32 s93, s8, 0xfffffd00
	s_mov_b32 m0, s16
	v_add_u32_e32 v164, s93, v231
	v_med3_i32 v164, v164, 0, s40
	v_lshl_or_b32 v164, v164, 7, v222
	global_load_lds_dwordx4 v164, s[24:25]
	s_add_i32 m0, s16, 0x400
	v_add_u32_e32 v165, s93, v232
	v_med3_i32 v165, v165, 0, s40
	v_lshl_or_b32 v165, v165, 7, v222
	global_load_lds_dwordx4 v165, s[24:25]
	s_waitcnt vmcnt(8)
	v_add_u32_e32 v154, s12, v225
	v_add_u32_e32 v155, s12, v226
	v_add_u32_e32 v156, s12, v227
	v_add_u32_e32 v157, s12, v228
	ds_read_b64_tr_b16 v[88:89], v154
	ds_read_b64_tr_b16 v[90:91], v155
	ds_read_b64_tr_b16 v[92:93], v156
	ds_read_b64_tr_b16 v[94:95], v157
	v_mfma_f32_16x16x16_bf16 v[96:99], v[202:203], v[20:21], v[96:99]
	v_mfma_f32_16x16x16_bf16 v[100:103], v[204:205], v[20:21], v[100:103]
	v_mfma_f32_16x16x16_bf16 v[104:107], v[206:207], v[20:21], v[104:107]
	v_mfma_f32_16x16x16_bf16 v[108:111], v[208:209], v[20:21], v[108:111]
	v_max3_f32 v186, v186, v51, v52
	v_max3_f32 v186, v186, v53, v54
	v_max3_f32 v186, v186, v55, v56
	v_max3_f32 v186, v186, v57, v58
	v_max3_f32 v186, v186, v59, v60
	v_max3_f32 v186, v186, v61, v62
	v_max3_f32 v186, v186, v63, v64
	v_max3_f32 v186, v186, v65, v66
	v_max3_f32 v186, v186, v67, v68
	v_max3_f32 v186, v186, v69, v70
	v_max_f32_e32 v186, v186, v71
	v_mov_b32_e32 v146, v186
	s_nop 1
	v_permlane16_swap_b32_e32 v186, v146
	v_max_f32_e32 v186, v186, v146
	v_mov_b32_e32 v146, v186
	s_nop 1
	v_permlane32_swap_b32_e32 v186, v146
	v_max_f32_e32 v186, v186, v146
	v_pk_add_f32 v[36:37], v[36:37], v[186:187] op_sel_hi:[1,0] neg_lo:[0,1] neg_hi:[0,1]
	v_pk_add_f32 v[38:39], v[38:39], v[186:187] op_sel_hi:[1,0] neg_lo:[0,1] neg_hi:[0,1]
	v_pk_add_f32 v[40:41], v[40:41], v[186:187] op_sel_hi:[1,0] neg_lo:[0,1] neg_hi:[0,1]
	v_pk_add_f32 v[42:43], v[42:43], v[186:187] op_sel_hi:[1,0] neg_lo:[0,1] neg_hi:[0,1]
	v_exp_f32_e32 v36, v36
	v_exp_f32_e32 v37, v37
	v_exp_f32_e32 v38, v38
	v_exp_f32_e32 v39, v39
	v_pk_add_f32 v[44:45], v[44:45], v[186:187] op_sel_hi:[1,0] neg_lo:[0,1] neg_hi:[0,1]
	v_pk_add_f32 v[46:47], v[46:47], v[186:187] op_sel_hi:[1,0] neg_lo:[0,1] neg_hi:[0,1]
	v_exp_f32_e32 v40, v40
	v_exp_f32_e32 v41, v41
	v_exp_f32_e32 v42, v42
	v_exp_f32_e32 v43, v43
	s_waitcnt lgkmcnt(0)
	s_add_i32 s93, s8, 0xfffffe00
	s_mov_b32 m0, s12
	v_add_u32_e32 v164, s93, v231
	v_med3_i32 v164, v164, 0, s40
	v_lshl_or_b32 v164, v164, 7, v222
	global_load_lds_dwordx4 v164, s[24:25]
	s_add_i32 m0, s12, 0x400
	v_add_u32_e32 v165, s93, v232
	v_med3_i32 v165, v165, 0, s40
	v_lshl_or_b32 v165, v165, 7, v222
	global_load_lds_dwordx4 v165, s[24:25]
	s_waitcnt vmcnt(8)
	v_add_u32_e32 v154, s13, v225
	v_add_u32_e32 v155, s13, v226
	v_add_u32_e32 v156, s13, v227
	v_add_u32_e32 v157, s13, v228
	ds_read_b64_tr_b16 v[202:203], v154
	ds_read_b64_tr_b16 v[204:205], v155
	ds_read_b64_tr_b16 v[206:207], v156
	ds_read_b64_tr_b16 v[208:209], v157
	v_mfma_f32_16x16x16_bf16 v[96:99], v[88:89], v[24:25], v[96:99]
	v_mfma_f32_16x16x16_bf16 v[100:103], v[90:91], v[24:25], v[100:103]
	v_mfma_f32_16x16x16_bf16 v[104:107], v[92:93], v[24:25], v[104:107]
	v_mfma_f32_16x16x16_bf16 v[108:111], v[94:95], v[24:25], v[108:111]
	v_pk_add_f32 v[48:49], v[48:49], v[186:187] op_sel_hi:[1,0] neg_lo:[0,1] neg_hi:[0,1]
	v_pk_add_f32 v[50:51], v[50:51], v[186:187] op_sel_hi:[1,0] neg_lo:[0,1] neg_hi:[0,1]
	v_exp_f32_e32 v44, v44
	v_exp_f32_e32 v45, v45
	v_exp_f32_e32 v46, v46
	v_exp_f32_e32 v47, v47
	v_pk_add_f32 v[52:53], v[52:53], v[186:187] op_sel_hi:[1,0] neg_lo:[0,1] neg_hi:[0,1]
	v_pk_add_f32 v[54:55], v[54:55], v[186:187] op_sel_hi:[1,0] neg_lo:[0,1] neg_hi:[0,1]
	v_exp_f32_e32 v48, v48
	v_exp_f32_e32 v49, v49
	v_exp_f32_e32 v50, v50
	v_exp_f32_e32 v51, v51
	v_pk_add_f32 v[56:57], v[56:57], v[186:187] op_sel_hi:[1,0] neg_lo:[0,1] neg_hi:[0,1]
	v_pk_add_f32 v[58:59], v[58:59], v[186:187] op_sel_hi:[1,0] neg_lo:[0,1] neg_hi:[0,1]
	v_exp_f32_e32 v52, v52
	v_exp_f32_e32 v53, v53
	v_exp_f32_e32 v54, v54
	v_exp_f32_e32 v55, v55
	v_pk_add_f32 v[60:61], v[60:61], v[186:187] op_sel_hi:[1,0] neg_lo:[0,1] neg_hi:[0,1]
	v_pk_add_f32 v[62:63], v[62:63], v[186:187] op_sel_hi:[1,0] neg_lo:[0,1] neg_hi:[0,1]
	v_exp_f32_e32 v56, v56
	v_exp_f32_e32 v57, v57
	v_exp_f32_e32 v58, v58
	v_exp_f32_e32 v59, v59
	v_pk_add_f32 v[64:65], v[64:65], v[186:187] op_sel_hi:[1,0] neg_lo:[0,1] neg_hi:[0,1]
	v_pk_add_f32 v[66:67], v[66:67], v[186:187] op_sel_hi:[1,0] neg_lo:[0,1] neg_hi:[0,1]
	v_exp_f32_e32 v60, v60
	v_exp_f32_e32 v61, v61
	v_exp_f32_e32 v62, v62
	v_exp_f32_e32 v63, v63
	v_pk_add_f32 v[68:69], v[68:69], v[186:187] op_sel_hi:[1,0] neg_lo:[0,1] neg_hi:[0,1]
	s_waitcnt lgkmcnt(0)
	s_add_i32 s93, s8, 0xffffff00
	s_mov_b32 m0, s13
	v_add_u32_e32 v164, s93, v231
	v_med3_i32 v164, v164, 0, s40
	v_lshl_or_b32 v164, v164, 7, v222
	global_load_lds_dwordx4 v164, s[24:25]
	s_add_i32 m0, s13, 0x400
	v_add_u32_e32 v165, s93, v232
	v_med3_i32 v165, v165, 0, s40
	v_lshl_or_b32 v165, v165, 7, v222
	global_load_lds_dwordx4 v165, s[24:25]
	s_waitcnt vmcnt(8)
	v_add_u32_e32 v154, s14, v225
	v_add_u32_e32 v155, s14, v226
	v_add_u32_e32 v156, s14, v227
	v_add_u32_e32 v157, s14, v228
	ds_read_b64_tr_b16 v[88:89], v154
	ds_read_b64_tr_b16 v[90:91], v155
	ds_read_b64_tr_b16 v[92:93], v156
	ds_read_b64_tr_b16 v[94:95], v157
	v_mfma_f32_16x16x16_bf16 v[96:99], v[202:203], v[28:29], v[96:99]
	v_mfma_f32_16x16x16_bf16 v[100:103], v[204:205], v[28:29], v[100:103]
	v_mfma_f32_16x16x16_bf16 v[104:107], v[206:207], v[28:29], v[104:107]
	v_mfma_f32_16x16x16_bf16 v[108:111], v[208:209], v[28:29], v[108:111]
	v_pk_add_f32 v[70:71], v[70:71], v[186:187] op_sel_hi:[1,0] neg_lo:[0,1] neg_hi:[0,1]
	v_exp_f32_e32 v64, v64
	v_exp_f32_e32 v65, v65
	v_exp_f32_e32 v66, v66
	v_exp_f32_e32 v67, v67
	v_exp_f32_e32 v68, v68
	v_exp_f32_e32 v69, v69
	v_exp_f32_e32 v70, v70
	v_exp_f32_e32 v71, v71
	s_nop 0
	v_pk_add_f32 v[146:147], v[36:37], v[38:39]
	v_pk_add_f32 v[148:149], v[40:41], v[42:43]
	v_pk_add_f32 v[146:147], v[146:147], v[44:45]
	v_pk_add_f32 v[148:149], v[148:149], v[46:47]
	v_pk_add_f32 v[146:147], v[146:147], v[48:49]
	v_pk_add_f32 v[148:149], v[148:149], v[50:51]
	v_pk_add_f32 v[146:147], v[146:147], v[52:53]
	v_pk_add_f32 v[148:149], v[148:149], v[54:55]
	v_pk_add_f32 v[146:147], v[146:147], v[56:57]
	v_pk_add_f32 v[148:149], v[148:149], v[58:59]
	v_pk_add_f32 v[146:147], v[146:147], v[60:61]
	v_pk_add_f32 v[148:149], v[148:149], v[62:63]
	v_pk_add_f32 v[146:147], v[146:147], v[64:65]
	v_pk_add_f32 v[148:149], v[148:149], v[66:67]
	v_pk_add_f32 v[146:147], v[146:147], v[68:69]
	v_pk_add_f32 v[148:149], v[148:149], v[70:71]
	s_nop 0
	v_pk_add_f32 v[146:147], v[146:147], v[148:149]
	s_nop 0
	v_add_f32_e32 v187, v146, v147
	v_cvt_pk_bf16_f32 v36, v36, v37
	s_waitcnt lgkmcnt(0)
	s_add_i32 s93, s8, 0
	s_mov_b32 m0, s14
	v_add_u32_e32 v164, s93, v231
	v_med3_i32 v164, v164, 0, s40
	v_lshl_or_b32 v164, v164, 7, v222
	global_load_lds_dwordx4 v164, s[24:25]
	s_add_i32 m0, s14, 0x400
	v_add_u32_e32 v165, s93, v232
	v_med3_i32 v165, v165, 0, s40
	v_lshl_or_b32 v165, v165, 7, v222
	global_load_lds_dwordx4 v165, s[24:25]
	s_waitcnt vmcnt(8)
	v_add_u32_e32 v72, s15, v225
	v_add_u32_e32 v73, s15, v226
	v_add_u32_e32 v74, s15, v227
	v_add_u32_e32 v75, s15, v228
	ds_read_b64_tr_b16 v[202:203], v72
	ds_read_b64_tr_b16 v[204:205], v73
	ds_read_b64_tr_b16 v[206:207], v74
	ds_read_b64_tr_b16 v[208:209], v75
	v_mfma_f32_16x16x16_bf16 v[96:99], v[88:89], v[32:33], v[96:99]
	v_mfma_f32_16x16x16_bf16 v[100:103], v[90:91], v[32:33], v[100:103]
	v_mfma_f32_16x16x16_bf16 v[104:107], v[92:93], v[32:33], v[104:107]
	v_mfma_f32_16x16x16_bf16 v[108:111], v[94:95], v[32:33], v[108:111]
	v_cvt_pk_bf16_f32 v37, v38, v39
	v_cvt_pk_bf16_f32 v40, v40, v41
	v_cvt_pk_bf16_f32 v41, v42, v43
	v_cvt_pk_bf16_f32 v44, v44, v45
	v_cvt_pk_bf16_f32 v45, v46, v47
	v_cvt_pk_bf16_f32 v48, v48, v49
	v_cvt_pk_bf16_f32 v49, v50, v51
	v_cvt_pk_bf16_f32 v52, v52, v53
	v_cvt_pk_bf16_f32 v53, v54, v55
	v_cvt_pk_bf16_f32 v56, v56, v57
	v_cvt_pk_bf16_f32 v57, v58, v59
	v_cvt_pk_bf16_f32 v60, v60, v61
	v_cvt_pk_bf16_f32 v61, v62, v63
	v_cvt_pk_bf16_f32 v64, v64, v65
	v_cvt_pk_bf16_f32 v65, v66, v67
	v_cvt_pk_bf16_f32 v68, v68, v69
	v_cvt_pk_bf16_f32 v69, v70, v71
	v_mov_b32_e32 v146, v187
	s_nop 1
	v_permlane16_swap_b32_e32 v187, v146
	v_add_f32_e32 v187, v187, v146
	v_mov_b32_e32 v146, v187
	s_nop 1
	v_permlane32_swap_b32_e32 v187, v146
	v_add_f32_e32 v187, v187, v146
	s_waitcnt lgkmcnt(0)
	s_add_i32 s93, s8, 0x100
	s_mov_b32 m0, s15
	v_add_u32_e32 v164, s93, v231
	v_med3_i32 v164, v164, 0, s40
	v_lshl_or_b32 v164, v164, 7, v222
	global_load_lds_dwordx4 v164, s[24:25]
	s_add_i32 m0, s15, 0x400
	v_add_u32_e32 v165, s93, v232
	v_med3_i32 v165, v165, 0, s40
	v_lshl_or_b32 v165, v165, 7, v222
	global_load_lds_dwordx4 v165, s[24:25]
	s_waitcnt vmcnt(8)
	v_add_u32_e32 v72, s16, v225
	v_add_u32_e32 v73, s16, v226
	v_add_u32_e32 v74, s16, v227
	v_add_u32_e32 v75, s16, v228
	ds_read_b64_tr_b16 v[88:89], v72
	ds_read_b64_tr_b16 v[90:91], v73
	ds_read_b64_tr_b16 v[92:93], v74
	ds_read_b64_tr_b16 v[94:95], v75
	v_mfma_f32_16x16x16_bf16 v[112:115], v[202:203], v[36:37], 0
	v_mfma_f32_16x16x16_bf16 v[116:119], v[204:205], v[36:37], 0
	v_mfma_f32_16x16x16_bf16 v[120:123], v[206:207], v[36:37], 0
	v_mfma_f32_16x16x16_bf16 v[124:127], v[208:209], v[36:37], 0
	s_waitcnt lgkmcnt(0)
	v_max_f32_e32 v146, v144, v184
	v_sub_f32_e32 v148, v144, v146
	v_sub_f32_e32 v150, v184, v146
	v_exp_f32_e32 v148, v148
	v_exp_f32_e32 v150, v150
	v_mov_b32_e32 v184, v146
	v_mul_f32_e32 v185, v185, v150
	v_fmac_f32_e32 v185, v145, v148
	v_pk_mul_f32 v[96:97], v[150:151], v[96:97] op_sel_hi:[0,1]
	v_pk_mul_f32 v[98:99], v[150:151], v[98:99] op_sel_hi:[0,1]
	v_pk_mul_f32 v[100:101], v[150:151], v[100:101] op_sel_hi:[0,1]
	s_waitcnt lgkmcnt(0)
	s_add_i32 s93, s8, 0x200
	s_mov_b32 m0, s16
	v_add_u32_e32 v164, s93, v231
	v_med3_i32 v164, v164, 0, s40
	v_lshl_or_b32 v164, v164, 7, v222
	global_load_lds_dwordx4 v164, s[24:25]
	s_add_i32 m0, s16, 0x400
	v_add_u32_e32 v165, s93, v232
	v_med3_i32 v165, v165, 0, s40
	v_lshl_or_b32 v165, v165, 7, v222
	global_load_lds_dwordx4 v165, s[24:25]
	s_waitcnt vmcnt(8)
	v_add_u32_e32 v72, s12, v225
	v_add_u32_e32 v73, s12, v226
	v_add_u32_e32 v74, s12, v227
	v_add_u32_e32 v75, s12, v228
	ds_read_b64_tr_b16 v[202:203], v72
	ds_read_b64_tr_b16 v[204:205], v73
	ds_read_b64_tr_b16 v[206:207], v74
	ds_read_b64_tr_b16 v[208:209], v75
	v_mfma_f32_16x16x16_bf16 v[112:115], v[88:89], v[40:41], v[112:115]
	v_mfma_f32_16x16x16_bf16 v[116:119], v[90:91], v[40:41], v[116:119]
	v_mfma_f32_16x16x16_bf16 v[120:123], v[92:93], v[40:41], v[120:123]
	v_mfma_f32_16x16x16_bf16 v[124:127], v[94:95], v[40:41], v[124:127]
	v_pk_mul_f32 v[102:103], v[150:151], v[102:103] op_sel_hi:[0,1]
	v_pk_mul_f32 v[104:105], v[150:151], v[104:105] op_sel_hi:[0,1]
	v_pk_mul_f32 v[106:107], v[150:151], v[106:107] op_sel_hi:[0,1]
	v_pk_mul_f32 v[108:109], v[150:151], v[108:109] op_sel_hi:[0,1]
	v_pk_mul_f32 v[110:111], v[150:151], v[110:111] op_sel_hi:[0,1]
	v_pk_fma_f32 v[96:97], v[148:149], v[128:129], v[96:97] op_sel_hi:[0,1,1]
	v_pk_fma_f32 v[98:99], v[148:149], v[130:131], v[98:99] op_sel_hi:[0,1,1]
	v_pk_fma_f32 v[100:101], v[148:149], v[132:133], v[100:101] op_sel_hi:[0,1,1]
	v_pk_fma_f32 v[102:103], v[148:149], v[134:135], v[102:103] op_sel_hi:[0,1,1]
	v_pk_fma_f32 v[104:105], v[148:149], v[136:137], v[104:105] op_sel_hi:[0,1,1]
	v_pk_fma_f32 v[106:107], v[148:149], v[138:139], v[106:107] op_sel_hi:[0,1,1]
	v_pk_fma_f32 v[108:109], v[148:149], v[140:141], v[108:109] op_sel_hi:[0,1,1]
	s_waitcnt lgkmcnt(0)
	s_add_i32 s93, s8, 0x300
	s_mov_b32 m0, s12
	v_add_u32_e32 v164, s93, v231
	v_med3_i32 v164, v164, 0, s40
	v_lshl_or_b32 v164, v164, 7, v222
	global_load_lds_dwordx4 v164, s[24:25]
	s_add_i32 m0, s12, 0x400
	v_add_u32_e32 v165, s93, v232
	v_med3_i32 v165, v165, 0, s40
	v_lshl_or_b32 v165, v165, 7, v222
	global_load_lds_dwordx4 v165, s[24:25]
	s_waitcnt vmcnt(8)
	v_add_u32_e32 v72, s13, v225
	v_add_u32_e32 v73, s13, v226
	v_add_u32_e32 v74, s13, v227
	v_add_u32_e32 v75, s13, v228
	ds_read_b64_tr_b16 v[88:89], v72
	ds_read_b64_tr_b16 v[90:91], v73
	ds_read_b64_tr_b16 v[92:93], v74
	ds_read_b64_tr_b16 v[94:95], v75
	v_mfma_f32_16x16x16_bf16 v[112:115], v[202:203], v[44:45], v[112:115]
	v_mfma_f32_16x16x16_bf16 v[116:119], v[204:205], v[44:45], v[116:119]
	v_mfma_f32_16x16x16_bf16 v[120:123], v[206:207], v[44:45], v[120:123]
	v_mfma_f32_16x16x16_bf16 v[124:127], v[208:209], v[44:45], v[124:127]
	v_pk_fma_f32 v[110:111], v[148:149], v[142:143], v[110:111] op_sel_hi:[0,1,1]
	v_div_scale_f32 v147, s[94:95], v185, v185, 1.0
	v_rcp_f32_e32 v148, v147
	v_div_scale_f32 v149, vcc, 1.0, v185, 1.0
	v_fma_f32 v150, -v147, v148, 1.0
	v_fmac_f32_e32 v148, v150, v148
	v_mul_f32_e32 v150, v149, v148
	v_fma_f32 v151, -v147, v150, v149
	v_fmac_f32_e32 v150, v151, v148
	v_fma_f32 v147, -v147, v150, v149
	s_nop 1
	v_div_fmas_f32 v147, v147, v148, v150
	s_waitcnt lgkmcnt(0)
	s_add_i32 s93, s8, 0x400
	s_mov_b32 m0, s13
	v_add_u32_e32 v164, s93, v231
	v_med3_i32 v164, v164, 0, s40
	v_lshl_or_b32 v164, v164, 7, v222
	global_load_lds_dwordx4 v164, s[24:25]
	s_add_i32 m0, s13, 0x400
	v_add_u32_e32 v165, s93, v232
	v_med3_i32 v165, v165, 0, s40
	v_lshl_or_b32 v165, v165, 7, v222
	global_load_lds_dwordx4 v165, s[24:25]
	s_waitcnt vmcnt(8)
	v_add_u32_e32 v72, s14, v225
	v_add_u32_e32 v73, s14, v226
	v_add_u32_e32 v74, s14, v227
	v_add_u32_e32 v75, s14, v228
	ds_read_b64_tr_b16 v[202:203], v72
	ds_read_b64_tr_b16 v[204:205], v73
	ds_read_b64_tr_b16 v[206:207], v74
	ds_read_b64_tr_b16 v[208:209], v75
	v_mfma_f32_16x16x16_bf16 v[112:115], v[88:89], v[48:49], v[112:115]
	v_mfma_f32_16x16x16_bf16 v[116:119], v[90:91], v[48:49], v[116:119]
	v_mfma_f32_16x16x16_bf16 v[120:123], v[92:93], v[48:49], v[120:123]
	v_mfma_f32_16x16x16_bf16 v[124:127], v[94:95], v[48:49], v[124:127]
	v_div_fixup_f32 v152, v147, v185, 1.0
	v_pk_mul_f32 v[96:97], v[152:153], v[96:97] op_sel_hi:[0,1]
	v_pk_mul_f32 v[98:99], v[152:153], v[98:99] op_sel_hi:[0,1]
	v_pk_mul_f32 v[100:101], v[152:153], v[100:101] op_sel_hi:[0,1]
	v_pk_mul_f32 v[102:103], v[152:153], v[102:103] op_sel_hi:[0,1]
	v_pk_mul_f32 v[104:105], v[152:153], v[104:105] op_sel_hi:[0,1]
	v_pk_mul_f32 v[106:107], v[152:153], v[106:107] op_sel_hi:[0,1]
	v_pk_mul_f32 v[108:109], v[152:153], v[108:109] op_sel_hi:[0,1]
	v_pk_mul_f32 v[110:111], v[152:153], v[110:111] op_sel_hi:[0,1]
	v_mul_f32_e32 v155, v97, v97
	v_mul_f32_e32 v156, v99, v99
	v_fmac_f32_e32 v155, v96, v96
	s_waitcnt lgkmcnt(0)
	s_add_i32 s93, s79, 0
	s_mov_b32 m0, s14
	v_add_u32_e32 v164, s93, v162
	v_lshl_or_b32 v164, v164, 7, v220
	global_load_lds_dwordx4 v164, s[30:31]
	s_add_i32 m0, s14, 0x400
	v_add_u32_e32 v165, s93, v163
	v_lshl_or_b32 v165, v165, 7, v221
	global_load_lds_dwordx4 v165, s[30:31]
	s_waitcnt vmcnt(8)
	v_add_u32_e32 v72, s15, v225
	v_add_u32_e32 v73, s15, v226
	v_add_u32_e32 v74, s15, v227
	v_add_u32_e32 v75, s15, v228
	ds_read_b64_tr_b16 v[88:89], v72
	ds_read_b64_tr_b16 v[90:91], v73
	ds_read_b64_tr_b16 v[92:93], v74
	ds_read_b64_tr_b16 v[94:95], v75
	v_mfma_f32_16x16x16_bf16 v[112:115], v[202:203], v[52:53], v[112:115]
	v_mfma_f32_16x16x16_bf16 v[116:119], v[204:205], v[52:53], v[116:119]
	v_mfma_f32_16x16x16_bf16 v[120:123], v[206:207], v[52:53], v[120:123]
	v_mfma_f32_16x16x16_bf16 v[124:127], v[208:209], v[52:53], v[124:127]
	v_fmac_f32_e32 v156, v98, v98
	v_add_f32_e32 v154, v155, v156
	v_mul_f32_e32 v155, v101, v101
	v_mul_f32_e32 v156, v103, v103
	v_fmac_f32_e32 v155, v100, v100
	v_fmac_f32_e32 v156, v102, v102
	v_add_f32_e32 v155, v155, v156
	v_add_f32_e32 v154, v154, v155
	v_mul_f32_e32 v155, v105, v105
	v_mul_f32_e32 v156, v107, v107
	v_fmac_f32_e32 v155, v104, v104
	v_fmac_f32_e32 v156, v106, v106
	s_waitcnt lgkmcnt(0)
	s_add_i32 s93, s79, 16
	s_mov_b32 m0, s15
	v_add_u32_e32 v164, s93, v162
	v_lshl_or_b32 v164, v164, 7, v220
	global_load_lds_dwordx4 v164, s[30:31]
	s_add_i32 m0, s15, 0x400
	v_add_u32_e32 v165, s93, v163
	v_lshl_or_b32 v165, v165, 7, v221
	global_load_lds_dwordx4 v165, s[30:31]
	s_waitcnt vmcnt(8)
	v_add_u32_e32 v72, s16, v225
	v_add_u32_e32 v73, s16, v226
	v_add_u32_e32 v74, s16, v227
	v_add_u32_e32 v75, s16, v228
	ds_read_b64_tr_b16 v[202:203], v72
	ds_read_b64_tr_b16 v[204:205], v73
	ds_read_b64_tr_b16 v[206:207], v74
	ds_read_b64_tr_b16 v[208:209], v75
	v_mfma_f32_16x16x16_bf16 v[112:115], v[88:89], v[56:57], v[112:115]
	v_mfma_f32_16x16x16_bf16 v[116:119], v[90:91], v[56:57], v[116:119]
	v_mfma_f32_16x16x16_bf16 v[120:123], v[92:93], v[56:57], v[120:123]
	v_mfma_f32_16x16x16_bf16 v[124:127], v[94:95], v[56:57], v[124:127]
	v_add_f32_e32 v155, v155, v156
	v_add_f32_e32 v154, v154, v155
	v_mul_f32_e32 v155, v109, v109
	v_mul_f32_e32 v156, v111, v111
	v_fmac_f32_e32 v155, v108, v108
	v_fmac_f32_e32 v156, v110, v110
	v_add_f32_e32 v155, v155, v156
	v_add_f32_e32 v154, v154, v155
	v_cvt_pk_bf16_f32 v96, v96, v97
	v_cvt_pk_bf16_f32 v97, v98, v99
	v_cvt_pk_bf16_f32 v100, v100, v101
	v_cvt_pk_bf16_f32 v101, v102, v103
	s_waitcnt lgkmcnt(0)
	s_add_i32 s93, s79, 0xffffffc0
	s_mov_b32 m0, s16
	v_add_u32_e32 v164, s93, v162
	v_med3_i32 v164, v164, 0, s41
	v_lshl_or_b32 v164, v164, 7, v220
	global_load_lds_dwordx4 v164, s[34:35]
	s_add_i32 m0, s16, 0x400
	v_add_u32_e32 v165, s93, v163
	v_med3_i32 v165, v165, 0, s41
	v_lshl_or_b32 v165, v165, 7, v221
	global_load_lds_dwordx4 v165, s[34:35]
	s_waitcnt vmcnt(8)
	v_add_u32_e32 v72, s12, v225
	v_add_u32_e32 v73, s12, v226
	v_add_u32_e32 v74, s12, v227
	v_add_u32_e32 v75, s12, v228
	ds_read_b64_tr_b16 v[88:89], v72
	ds_read_b64_tr_b16 v[90:91], v73
	ds_read_b64_tr_b16 v[92:93], v74
	ds_read_b64_tr_b16 v[94:95], v75
	v_mfma_f32_16x16x16_bf16 v[112:115], v[202:203], v[60:61], v[112:115]
	v_mfma_f32_16x16x16_bf16 v[116:119], v[204:205], v[60:61], v[116:119]
	v_mfma_f32_16x16x16_bf16 v[120:123], v[206:207], v[60:61], v[120:123]
	v_mfma_f32_16x16x16_bf16 v[124:127], v[208:209], v[60:61], v[124:127]
	v_cvt_pk_bf16_f32 v104, v104, v105
	v_cvt_pk_bf16_f32 v105, v106, v107
	v_cvt_pk_bf16_f32 v108, v108, v109
	v_cvt_pk_bf16_f32 v109, v110, v111
	v_add_u32_e32 v157, s42, v188
	s_lshl_b32 s90, s43, 7
	v_lshlrev_b32_e32 v158, 11, v157
	v_add3_u32 v158, v158, s90, v233
	v_mov_b32_e32 v76, v96
	v_mov_b32_e32 v77, v97
	v_mov_b32_e32 v78, v100
	v_mov_b32_e32 v79, v101
	s_waitcnt lgkmcnt(0)
	s_add_i32 s93, s79, 0xffffffd0
	s_mov_b32 m0, s12
	v_add_u32_e32 v164, s93, v162
	v_med3_i32 v164, v164, 0, s41
	v_lshl_or_b32 v164, v164, 7, v220
	global_load_lds_dwordx4 v164, s[34:35]
	s_add_i32 m0, s12, 0x400
	v_add_u32_e32 v165, s93, v163
	v_med3_i32 v165, v165, 0, s41
	v_lshl_or_b32 v165, v165, 7, v221
	global_load_lds_dwordx4 v165, s[34:35]
	s_waitcnt vmcnt(8)
	v_add_u32_e32 v72, s13, v225
	v_add_u32_e32 v73, s13, v226
	v_add_u32_e32 v74, s13, v227
	v_add_u32_e32 v75, s13, v228
	ds_read_b64_tr_b16 v[202:203], v72
	ds_read_b64_tr_b16 v[204:205], v73
	ds_read_b64_tr_b16 v[206:207], v74
	ds_read_b64_tr_b16 v[208:209], v75
	v_mfma_f32_16x16x16_bf16 v[112:115], v[88:89], v[64:65], v[112:115]
	v_mfma_f32_16x16x16_bf16 v[116:119], v[90:91], v[64:65], v[116:119]
	v_mfma_f32_16x16x16_bf16 v[120:123], v[92:93], v[64:65], v[120:123]
	v_mfma_f32_16x16x16_bf16 v[124:127], v[94:95], v[64:65], v[124:127]
	s_nop 1
	v_permlane16_swap_b32_e32 v76, v78
	v_permlane16_swap_b32_e32 v77, v79
	v_mov_b32_e32 v80, v104
	v_mov_b32_e32 v81, v105
	v_mov_b32_e32 v82, v108
	v_mov_b32_e32 v83, v109
	s_nop 1
	v_permlane16_swap_b32_e32 v80, v82
	v_permlane16_swap_b32_e32 v81, v83
	v_mov_b32_e32 v155, v154
	s_nop 1
	v_permlane16_swap_b32_e32 v154, v155
	s_waitcnt lgkmcnt(0)
	s_add_i32 s93, s79, 0xffffffe0
	s_mov_b32 m0, s13
	v_add_u32_e32 v164, s93, v162
	v_med3_i32 v164, v164, 0, s41
	v_lshl_or_b32 v164, v164, 7, v220
	global_load_lds_dwordx4 v164, s[34:35]
	s_add_i32 m0, s13, 0x400
	v_add_u32_e32 v165, s93, v163
	v_med3_i32 v165, v165, 0, s41
	v_lshl_or_b32 v165, v165, 7, v221
	global_load_lds_dwordx4 v165, s[34:35]
	v_mfma_f32_16x16x16_bf16 v[112:115], v[202:203], v[68:69], v[112:115]
	v_mfma_f32_16x16x16_bf16 v[116:119], v[204:205], v[68:69], v[116:119]
	v_mfma_f32_16x16x16_bf16 v[120:123], v[206:207], v[68:69], v[120:123]
	v_mfma_f32_16x16x16_bf16 v[124:127], v[208:209], v[68:69], v[124:127]
	v_add_f32_e32 v154, v154, v155
	v_mov_b32_e32 v155, v154
	s_nop 1
	v_permlane32_swap_b32_e32 v154, v155
	v_add_f32_e32 v154, v154, v155
	v_mul_u32_u24_e32 v157, 48, v157
	s_lshl_b32 s90, s43, 2
	v_add_u32_e32 v157, s90, v157
	s_nop 1
	global_store_dwordx4 v158, v[76:79], s[48:49] offset:0
	global_store_dwordx4 v158, v[80:83], s[48:49] offset:64
	s_and_saveexec_b64 s[80:81], s[74:75]
	global_store_dword v157, v154, s[50:51]
	s_mov_b64 exec, s[80:81]
	s_waitcnt lgkmcnt(0)
	v_max_f32_e32 v146, v182, v186
	v_sub_f32_e32 v148, v182, v146
	v_sub_f32_e32 v150, v186, v146
	v_exp_f32_e32 v148, v148
	v_exp_f32_e32 v150, v150
	v_mov_b32_e32 v186, v146
	v_mul_f32_e32 v187, v187, v150
	v_fmac_f32_e32 v187, v183, v148
	v_pk_mul_f32 v[112:113], v[150:151], v[112:113] op_sel_hi:[0,1]
	v_pk_mul_f32 v[114:115], v[150:151], v[114:115] op_sel_hi:[0,1]
	v_pk_mul_f32 v[116:117], v[150:151], v[116:117] op_sel_hi:[0,1]
	v_pk_mul_f32 v[118:119], v[150:151], v[118:119] op_sel_hi:[0,1]
	v_pk_mul_f32 v[120:121], v[150:151], v[120:121] op_sel_hi:[0,1]
	v_pk_mul_f32 v[122:123], v[150:151], v[122:123] op_sel_hi:[0,1]
	v_pk_mul_f32 v[124:125], v[150:151], v[124:125] op_sel_hi:[0,1]
	v_pk_mul_f32 v[126:127], v[150:151], v[126:127] op_sel_hi:[0,1]
	v_pk_fma_f32 v[112:113], v[148:149], v[166:167], v[112:113] op_sel_hi:[0,1,1]
	v_pk_fma_f32 v[114:115], v[148:149], v[168:169], v[114:115] op_sel_hi:[0,1,1]
	v_pk_fma_f32 v[116:117], v[148:149], v[170:171], v[116:117] op_sel_hi:[0,1,1]
	v_pk_fma_f32 v[118:119], v[148:149], v[172:173], v[118:119] op_sel_hi:[0,1,1]
	v_pk_fma_f32 v[120:121], v[148:149], v[174:175], v[120:121] op_sel_hi:[0,1,1]
	v_pk_fma_f32 v[122:123], v[148:149], v[176:177], v[122:123] op_sel_hi:[0,1,1]
	v_pk_fma_f32 v[124:125], v[148:149], v[178:179], v[124:125] op_sel_hi:[0,1,1]
	v_pk_fma_f32 v[126:127], v[148:149], v[180:181], v[126:127] op_sel_hi:[0,1,1]
	v_div_scale_f32 v147, s[94:95], v187, v187, 1.0
	v_rcp_f32_e32 v148, v147
	v_div_scale_f32 v149, vcc, 1.0, v187, 1.0
	v_fma_f32 v150, -v147, v148, 1.0
	v_fmac_f32_e32 v148, v150, v148
	v_mul_f32_e32 v150, v149, v148
	v_fma_f32 v151, -v147, v150, v149
	v_fmac_f32_e32 v150, v151, v148
	v_fma_f32 v147, -v147, v150, v149
	s_nop 1
	v_div_fmas_f32 v147, v147, v148, v150
	v_div_fixup_f32 v152, v147, v187, 1.0
	v_pk_mul_f32 v[112:113], v[152:153], v[112:113] op_sel_hi:[0,1]
	v_pk_mul_f32 v[114:115], v[152:153], v[114:115] op_sel_hi:[0,1]
	v_pk_mul_f32 v[116:117], v[152:153], v[116:117] op_sel_hi:[0,1]
	v_pk_mul_f32 v[118:119], v[152:153], v[118:119] op_sel_hi:[0,1]
	v_pk_mul_f32 v[120:121], v[152:153], v[120:121] op_sel_hi:[0,1]
	v_pk_mul_f32 v[122:123], v[152:153], v[122:123] op_sel_hi:[0,1]
	v_pk_mul_f32 v[124:125], v[152:153], v[124:125] op_sel_hi:[0,1]
	v_pk_mul_f32 v[126:127], v[152:153], v[126:127] op_sel_hi:[0,1]
	v_mul_f32_e32 v155, v113, v113
	v_mul_f32_e32 v156, v115, v115
	v_fmac_f32_e32 v155, v112, v112
	v_fmac_f32_e32 v156, v114, v114
	v_add_f32_e32 v154, v155, v156
	v_mul_f32_e32 v155, v117, v117
	v_mul_f32_e32 v156, v119, v119
	v_fmac_f32_e32 v155, v116, v116
	v_fmac_f32_e32 v156, v118, v118
	v_add_f32_e32 v155, v155, v156
	v_add_f32_e32 v154, v154, v155
	v_mul_f32_e32 v155, v121, v121
	v_mul_f32_e32 v156, v123, v123
	v_fmac_f32_e32 v155, v120, v120
	v_fmac_f32_e32 v156, v122, v122
	v_add_f32_e32 v155, v155, v156
	v_add_f32_e32 v154, v154, v155
	v_mul_f32_e32 v155, v125, v125
	v_mul_f32_e32 v156, v127, v127
	v_fmac_f32_e32 v155, v124, v124
	v_fmac_f32_e32 v156, v126, v126
	v_add_f32_e32 v155, v155, v156
	v_add_f32_e32 v154, v154, v155
	v_cvt_pk_bf16_f32 v112, v112, v113
	v_cvt_pk_bf16_f32 v113, v114, v115
	v_cvt_pk_bf16_f32 v116, v116, v117
	v_cvt_pk_bf16_f32 v117, v118, v119
	v_cvt_pk_bf16_f32 v120, v120, v121
	v_cvt_pk_bf16_f32 v121, v122, v123
	v_cvt_pk_bf16_f32 v124, v124, v125
	v_cvt_pk_bf16_f32 v125, v126, v127
	v_add_u32_e32 v157, s42, v189
	s_lshl_b32 s90, s43, 7
	v_lshlrev_b32_e32 v158, 11, v157
	v_add3_u32 v158, v158, s90, v233
	v_mov_b32_e32 v160, v112
	v_mov_b32_e32 v161, v113
	v_mov_b32_e32 v162, v116
	v_mov_b32_e32 v163, v117
	s_nop 1
	v_permlane16_swap_b32_e32 v160, v162
	v_permlane16_swap_b32_e32 v161, v163
	s_nop 1
	global_store_dwordx4 v158, v[160:163], s[48:49] offset:0
	s_nop 1
	v_mov_b32_e32 v160, v120
	v_mov_b32_e32 v161, v121
	v_mov_b32_e32 v162, v124
	v_mov_b32_e32 v163, v125
	s_nop 1
	v_permlane16_swap_b32_e32 v160, v162
	v_permlane16_swap_b32_e32 v161, v163
	s_nop 1
	global_store_dwordx4 v158, v[160:163], s[48:49] offset:64
	s_nop 1
	v_mov_b32_e32 v155, v154
	s_nop 1
	v_permlane16_swap_b32_e32 v154, v155
	v_add_f32_e32 v154, v154, v155
	v_mov_b32_e32 v155, v154
	s_nop 1
	v_permlane32_swap_b32_e32 v154, v155
	v_add_f32_e32 v154, v154, v155
	v_mul_u32_u24_e32 v157, 48, v157
	s_lshl_b32 s90, s43, 2
	v_add_u32_e32 v157, s90, v157
	s_and_saveexec_b64 s[80:81], s[74:75]
	global_store_dword v157, v154, s[50:51]
	s_mov_b64 exec, s[80:81]
	s_waitcnt lgkmcnt(0)
	s_barrier
	s_mov_b32 s90, s14
	s_mov_b32 s91, s15
	s_mov_b32 s92, s16
	s_mov_b32 s93, s12
	s_mov_b32 s97, s13
	s_mov_b32 s12, s90
	s_mov_b32 s13, s91
	s_mov_b32 s14, s92
	s_mov_b32 s15, s93
	s_mov_b32 s16, s97
	s_mov_b64 s[18:19], s[30:31]
	s_mov_b64 s[20:21], s[34:35]
	s_mov_b64 s[24:25], s[36:37]
	s_mov_b32 s38, s39
	s_mov_b32 s40, s41
	s_mov_b32 s42, s44
	s_mov_b32 s43, s45
	s_add_i32 s11, s11, s66
	s_cmpk_lt_u32 s11, 0x900
	s_cbranch_scc1 .Latt_unit
	v_readlane_b32 s0, v244, 20
	s_bfe_u32 s3, s0, 0x20006
